# P4 (MLA q/k norm + rotary) item loop hand-written: software-pipelined loads, DPP reductions
# speedup vs baseline: 1.0648x; 1.0099x over previous
; __device__ __forceinline__ float shfl_xor_l(float v, int o, int lane) { return __builtin_bit_cast(float, __builtin_amdgcn_ds_bpermute((lane ^ o) << 2, __builtin_bit_cast(int, v))); }
; #define INP(i) (*(const float* const volatile __attribute__((address_space(4)))*)((const __attribute__((address_space(4))) char*)__builtin_amdgcn_kernarg_segment_ptr() + 8 * (i)))
; __global__ void __launch_bounds__(NTHREADS, 2) mega_fwd(Args args) {
;     ...
;         PHASE_IDS;
;         const bf16* Z = (const bf16*)(ws + A_Z); const bf16* QF = (const bf16*)(ws + A_QF); const bf16* KV = (const bf16*)(ws + A_KV);
;         const float2* rope = (const float2*)(ws + S_ROPE);
;         const float qsc = 0.10206207261596577f * LOG2E;
;         for (int it = gw; it < 2 * T * 2; it += NGW) {
;             const int which = it >= T * 2, j = which ? it - T * 2 : it, row = j >> 1, h = (j & 1) * 4 + (lane >> 4), sub = lane & 15;
;             const bool act = sub < 12;
;             const bf16* src = !which ? QF + (size_t)row * 768 + h * 96 + sub * 8 : (sub < 8 ? KV + (size_t)row * 1024 + h * 128 + sub * 8 : Z + (size_t)row * ZW + 1152 + (sub - 8) * 8);
;             const u32x4 zero4 = {0u, 0u, 0u, 0u};
;             const u32x4 v = act ? *(const u32x4*)src : zero4;
;             float ss = chunk_ss(v); ss += shfl_xor_l(ss, 1, lane); ss += shfl_xor_l(ss, 2, lane); ss += shfl_xor_l(ss, 4, lane); ss += shfl_xor_l(ss, 8, lane);
;             const float r = (1.0f / sqrtf(ss * (1.f / 96.f) + EPS)) * (which ? 1.0f : qsc);
;             const float* gain = which ? INP(13) : INP(12);
;             u32x4 pv;
;             pv.x = __builtin_amdgcn_ds_bpermute((lane ^ 2) << 2, v.x); pv.y = __builtin_amdgcn_ds_bpermute((lane ^ 2) << 2, v.y);
;             pv.z = __builtin_amdgcn_ds_bpermute((lane ^ 2) << 2, v.z); pv.w = __builtin_amdgcn_ds_bpermute((lane ^ 2) << 2, v.w);
;             if (act) {
;                 bf16* dst = (bf16*)(ws + (which ? A_KB : A_QB)) + (size_t)row * 768 + h * 96 + sub * 8;
.LBB0_444:
	s_load_dwordx2 s[2:3], s[82:83], 0x110
	s_waitcnt lgkmcnt(0)
	s_cmp_lt_i32 s2, 5
	s_cselect_b64 s[16:17], -1, 0
	s_and_b64 s[2:3], s[16:17], s[4:5]
	s_load_dwordx4 s[4:7], s[82:83], 0x100
	s_cmpk_lt_i32 s84, 0x400
	s_cselect_b64 s[14:15], -1, 0
	s_waitcnt lgkmcnt(0)
	s_add_u32 s4, s6, 0x1aa00000
	s_addc_u32 s5, s7, 0
	v_writelane_b32 v252, s4, 39
	s_andn2_b64 vcc, exec, s[2:3]
	s_nop 0
	v_writelane_b32 v252, s5, 40
	s_cbranch_vccnz .LBB0_465
	v_readlane_b32 s6, v252, 18
	v_mov_b32_e32 v9, v212
	v_readlane_b32 s7, v252, 19
	s_load_dword s2, s[6:7], 0x0
	v_readfirstlane_b32 s4, v9
	s_lshl_b32 s3, s84, 3
	s_ashr_i32 s4, s4, 6
	s_add_i32 s3, s4, s3
	s_cmp_gt_i32 s3, 0x1ffff
	s_cbranch_scc1 .LBB0_462
	s_load_dwordx4 s[8:11], s[82:83], 0x100
	v_and_b32_e32 v1, 15, v9
	v_and_b32_e32 v0, 63, v9
	v_mov_b32_e32 v11, 0
	v_lshlrev_b32_e32 v10, 4, v1
	v_lshlrev_b32_e32 v2, 6, v9
	v_lshlrev_b32_e32 v8, 3, v1
	s_waitcnt lgkmcnt(0)
	v_lshl_add_u64 v[12:13], s[10:11], 0, v[10:11]
	v_lshlrev_b32_e32 v0, 2, v0
	v_and_b32_e32 v10, 64, v2
	v_xor_b32_e32 v27, 4, v0
	v_xor_b32_e32 v28, 8, v0
	v_xor_b32_e32 v29, 16, v0
	v_xor_b32_e32 v30, 32, v0
	v_xor_b32_e32 v0, 16, v8
	v_lshl_add_u64 v[2:3], s[10:11], 0, v[10:11]
	s_mov_b64 s[8:9], 0x3d00000
	v_bfe_u32 v26, v9, 4, 2
	v_cmp_gt_u32_e64 s[4:5], 12, v1
	v_cmp_lt_u32_e64 s[6:7], 7, v1
	v_lshl_add_u64 v[14:15], v[2:3], 0, s[8:9]
	v_cmp_gt_u32_e64 s[8:9], 10, v1
	s_lshl_b32 s28, s2, 3
	s_mov_b64 s[18:19], 0x8200880
	s_movk_i32 s29, 0x68
	v_mov_b32_e32 v31, 0x358637bd
	s_mov_b32 s30, 0xf800000
	v_mov_b32_e32 v32, 0x260
	v_lshlrev_b32_e32 v33, 2, v0
	s_mov_b32 s31, 0x17a00000
	v_lshlrev_b32_e32 v16, 1, v8
	v_mov_b32_e32 v34, 0xa00
	v_mov_b32_e32 v35, 0x3e16c740
	v_and_b32_e32 v1, 15, v212
	v_bfe_u32 v2, v212, 4, 2
	v_mul_u32_u24_e32 v3, 0xc0, v2
	v_lshl_add_u32 v3, v1, 4, v3
	v_lshlrev_b32_e32 v4, 8, v2
	v_lshl_add_u32 v4, v1, 4, v4
	v_lshlrev_b32_e32 v13, 4, v1
	v_add_u32_e32 v13, 0x880, v13
	v_and_b32_e32 v5, 1, v1
	v_lshlrev_b32_e32 v5, 6, v5
	v_mov_b32_e32 v14, 0x358637bd
	v_mov_b32_e32 v15, 1.5
	v_cmp_gt_u32_e64 s[10:11], 12, v1
	v_cmp_lt_u32_e64 s[6:7], 7, v1
	v_cmp_gt_u32_e64 s[8:9], 10, v1
	v_cmp_gt_u32_e64 s[32:33], 8, v1
	s_load_dwordx2 s[98:99], s[82:83], 0x108
	s_load_dwordx2 s[20:21], s[82:83], 0x60
	s_load_dwordx2 s[22:23], s[82:83], 0x68
	s_waitcnt lgkmcnt(0)
	v_min_u32_e32 v6, 11, v1
	v_lshlrev_b32_e32 v7, 5, v6
	v_xor_b32_e32 v6, 2, v6
	v_min_u32_e32 v6, 11, v6
	v_lshlrev_b32_e32 v8, 5, v6
	global_load_dwordx4 v[16:19], v7, s[20:21]
	global_load_dwordx4 v[20:23], v7, s[20:21] offset:16
	global_load_dwordx4 v[24:27], v8, s[20:21]
	global_load_dwordx4 v[28:31], v8, s[20:21] offset:16
	global_load_dwordx4 v[32:35], v7, s[22:23]
	global_load_dwordx4 v[36:39], v7, s[22:23] offset:16
	global_load_dwordx4 v[40:43], v8, s[22:23]
	global_load_dwordx4 v[44:47], v8, s[22:23] offset:16
	s_waitcnt vmcnt(0)
	v_mov_b32_e32 v6, 0x80000000
	v_cndmask_b32_e64 v6, 0, v6, s[8:9]
	v_xor_b32_e32 v24, v6, v24
	v_xor_b32_e32 v40, v6, v40
	v_xor_b32_e32 v25, v6, v25
	v_xor_b32_e32 v41, v6, v41
	v_xor_b32_e32 v26, v6, v26
	v_xor_b32_e32 v42, v6, v42
	v_xor_b32_e32 v27, v6, v27
	v_xor_b32_e32 v43, v6, v43
	v_xor_b32_e32 v28, v6, v28
	v_xor_b32_e32 v44, v6, v44
	v_xor_b32_e32 v29, v6, v29
	v_xor_b32_e32 v45, v6, v45
	v_xor_b32_e32 v30, v6, v30
	v_xor_b32_e32 v46, v6, v46
	v_xor_b32_e32 v31, v6, v31
	v_xor_b32_e32 v47, v6, v47
	s_and_b64 s[8:9], s[10:11], s[6:7]
	v_mov_b32_e32 v48, 0
	v_mov_b32_e32 v49, 0
	v_mov_b32_e32 v50, 0
	v_mov_b32_e32 v51, 0
	v_mov_b32_e32 v68, 0
	v_mov_b32_e32 v69, 0
	v_mov_b32_e32 v70, 0
	v_mov_b32_e32 v71, 0
	s_cmp_ge_i32 s3, 0x10000
	s_cbranch_scc1 .Lp4_q_done
	s_and_b32 s4, s3, 0xffff
	s_lshr_b32 s5, s4, 1
	s_and_b32 s4, s4, 1
	s_mul_i32 s12, s5, 0x600
	s_mul_i32 s13, s4, 0x300
	s_add_u32 s12, s12, s13
	s_add_u32 s20, s98, 0x11a00000
	s_addc_u32 s21, s99, 0
	s_add_u32 s20, s20, s12
	s_addc_u32 s21, s21, 0
	s_mov_b64 s[22:23], s[20:21]
	s_add_u32 s26, s98, 0x14a00000
	s_addc_u32 s27, s99, 0
	s_add_u32 s26, s26, s12
	s_addc_u32 s27, s27, 0
	s_lshl_b32 s13, s5, 7
	s_add_u32 s24, s98, 0x3d00000
	s_addc_u32 s25, s99, 0
	s_add_u32 s24, s24, s13
	s_addc_u32 s25, s25, 0
	s_mov_b64 exec, s[32:33]
	global_load_dwordx4 v[48:51], v3, s[20:21]
	s_mov_b64 exec, s[8:9]
	global_load_dwordx4 v[48:51], v3, s[22:23]
	s_mov_b64 exec, -1
	global_load_dwordx4 v[52:55], v5, s[24:25] offset:0
	global_load_dwordx4 v[56:59], v5, s[24:25] offset:16
	global_load_dwordx4 v[60:63], v5, s[24:25] offset:32
	global_load_dwordx4 v[64:67], v5, s[24:25] offset:48
	s_waitcnt vmcnt(0)
; #define UNPK8(v, f) do { f[0] = bflo(v.x); f[1] = bfhi(v.x); f[2] = bflo(v.y); f[3] = bfhi(v.y); f[4] = bflo(v.z); f[5] = bfhi(v.z); f[6] = bflo(v.w); f[7] = bfhi(v.w); } while (0)
; #define PACK8(v, f) do { v.x = pk2(f[0], f[1]); v.y = pk2(f[2], f[3]); v.z = pk2(f[4], f[5]); v.w = pk2(f[6], f[7]); } while (0)
; __global__ void __launch_bounds__(NTHREADS, 2) mega_fwd(Args args) {
;     ...
;         for (int it = gw; it < 2 * T * 2; it += NGW) {
;             const int which = it >= T * 2, j = which ? it - T * 2 : it, row = j >> 1, h = (j & 1) * 4 + (lane >> 4), sub = lane & 15;
;             const bool act = sub < 12;
;             const bf16* src = !which ? QF + (size_t)row * 768 + h * 96 + sub * 8 : (sub < 8 ? KV + (size_t)row * 1024 + h * 128 + sub * 8 : Z + (size_t)row * ZW + 1152 + (sub - 8) * 8);
;             const u32x4 zero4 = {0u, 0u, 0u, 0u};
;             const u32x4 v = act ? *(const u32x4*)src : zero4;
;             float ss = chunk_ss(v); ss += shfl_xor_l(ss, 1, lane); ss += shfl_xor_l(ss, 2, lane); ss += shfl_xor_l(ss, 4, lane); ss += shfl_xor_l(ss, 8, lane);
;             const float r = (1.0f / sqrtf(ss * (1.f / 96.f) + EPS)) * (which ? 1.0f : qsc);
;             const float* gain = which ? INP(13) : INP(12);
;             u32x4 pv;
;             pv.x = __builtin_amdgcn_ds_bpermute((lane ^ 2) << 2, v.x); pv.y = __builtin_amdgcn_ds_bpermute((lane ^ 2) << 2, v.y);
;             pv.z = __builtin_amdgcn_ds_bpermute((lane ^ 2) << 2, v.z); pv.w = __builtin_amdgcn_ds_bpermute((lane ^ 2) << 2, v.w);
;             if (act) {
;                 bf16* dst = (bf16*)(ws + (which ? A_KB : A_QB)) + (size_t)row * 768 + h * 96 + sub * 8;
;                 float f[8]; UNPK8(v, f);
;                 const float* g = gain + sub * 8;
; #pragma unroll
;                 for (int i = 0; i < 8; ++i) f[i] *= r * g[i];
;                 if (sub >= 8) {
;                     float pf_[8]; UNPK8(pv, pf_);
;                     const float* gp = gain + (sub ^ 2) * 8; const float2* cs = rope + (size_t)row * 16 + (sub & 1) * 8;
; #pragma unroll
;                     for (int i = 0; i < 8; ++i) { const float pn = pf_[i] * r * gp[i]; const float2 c = cs[i];
;                         f[i] = (sub < 10) ? (f[i] * c.x - pn * c.y) : (f[i] * c.x + pn * c.y); }
;                 }
;                 u32x4 o; PACK8(o, f); *(u32x4*)dst = o;
.Lp4_q_it0:
	s_add_i32 s18, s3, s28
	s_cmp_ge_i32 s18, 0x10000
	s_cbranch_scc1 .Lp4_q_last0
	s_and_b32 s4, s18, 0xffff
	s_lshr_b32 s5, s4, 1
	s_and_b32 s4, s4, 1
	s_mul_i32 s12, s5, 0x600
	s_mul_i32 s13, s4, 0x300
	s_add_u32 s12, s12, s13
	s_add_u32 s20, s98, 0x11a00000
	s_addc_u32 s21, s99, 0
	s_add_u32 s20, s20, s12
	s_addc_u32 s21, s21, 0
	s_mov_b64 s[22:23], s[20:21]
	s_add_u32 s30, s98, 0x14a00000
	s_addc_u32 s31, s99, 0
	s_add_u32 s30, s30, s12
	s_addc_u32 s31, s31, 0
	s_lshl_b32 s13, s5, 7
	s_add_u32 s24, s98, 0x3d00000
	s_addc_u32 s25, s99, 0
	s_add_u32 s24, s24, s13
	s_addc_u32 s25, s25, 0
	s_mov_b64 exec, s[32:33]
	global_load_dwordx4 v[68:71], v3, s[20:21]
	s_mov_b64 exec, s[8:9]
	global_load_dwordx4 v[68:71], v3, s[22:23]
	s_mov_b64 exec, -1
	global_load_dwordx4 v[72:75], v5, s[24:25] offset:0
	global_load_dwordx4 v[76:79], v5, s[24:25] offset:16
	global_load_dwordx4 v[80:83], v5, s[24:25] offset:32
	global_load_dwordx4 v[84:87], v5, s[24:25] offset:48
	v_lshlrev_b32_e32 v88, 16, v48
	v_and_b32_e32 v89, 0xffff0000, v48
	v_lshlrev_b32_e32 v90, 16, v49
	v_and_b32_e32 v91, 0xffff0000, v49
	v_lshlrev_b32_e32 v92, 16, v50
	v_and_b32_e32 v93, 0xffff0000, v50
	v_lshlrev_b32_e32 v94, 16, v51
	v_and_b32_e32 v95, 0xffff0000, v51
	v_mov_b32_dpp v96, v48 quad_perm:[2,3,0,1] row_mask:0xf bank_mask:0xf
	v_mov_b32_dpp v97, v49 quad_perm:[2,3,0,1] row_mask:0xf bank_mask:0xf
	v_mov_b32_dpp v98, v50 quad_perm:[2,3,0,1] row_mask:0xf bank_mask:0xf
	v_mov_b32_dpp v99, v51 quad_perm:[2,3,0,1] row_mask:0xf bank_mask:0xf
	v_mul_f32_e32 v108, v88, v88
	v_fmac_f32_e32 v108, v89, v89
	v_fmac_f32_e32 v108, v90, v90
	v_fmac_f32_e32 v108, v91, v91
	v_fmac_f32_e32 v108, v92, v92
	v_fmac_f32_e32 v108, v93, v93
	v_fmac_f32_e32 v108, v94, v94
	v_fmac_f32_e32 v108, v95, v95
	s_nop 1
	v_add_f32_dpp v109, v108, v108 quad_perm:[1,0,3,2] row_mask:0xf bank_mask:0xf
	s_nop 1
	v_add_f32_dpp v108, v109, v109 quad_perm:[2,3,0,1] row_mask:0xf bank_mask:0xf
	s_nop 1
	v_add_f32_dpp v109, v108, v108 row_half_mirror row_mask:0xf bank_mask:0xf
	s_nop 1
	v_add_f32_dpp v108, v109, v109 row_mirror row_mask:0xf bank_mask:0xf
	v_lshlrev_b32_e32 v100, 16, v96
	v_and_b32_e32 v101, 0xffff0000, v96
	v_lshlrev_b32_e32 v102, 16, v97
	v_and_b32_e32 v103, 0xffff0000, v97
	v_lshlrev_b32_e32 v104, 16, v98
	v_and_b32_e32 v105, 0xffff0000, v98
	v_lshlrev_b32_e32 v106, 16, v99
	v_and_b32_e32 v107, 0xffff0000, v99
	v_fmamk_f32 v109, v108, 0x3c2aaaab, v14
	v_rsq_f32_e32 v110, v109
	s_nop 0
	v_mul_f32_e32 v111, v109, v110
	v_mul_f32_e32 v111, v111, v110
	v_fma_f32 v111, v111, -0.5, v15
	v_mul_f32_e32 v110, v110, v111
	v_mul_f32_e32 v110, 0x3e16c740, v110
	v_mul_f32_e32 v112, v110, v16
	v_mul_f32_e32 v113, v110, v17
	v_mul_f32_e32 v114, v110, v18
	v_mul_f32_e32 v115, v110, v19
	v_mul_f32_e32 v116, v110, v20
	v_mul_f32_e32 v117, v110, v21
	v_mul_f32_e32 v118, v110, v22
	v_mul_f32_e32 v119, v110, v23
	v_mul_f32_e32 v88, v88, v112
	v_mul_f32_e32 v89, v89, v113
	v_mul_f32_e32 v90, v90, v114
	v_mul_f32_e32 v91, v91, v115
	v_mul_f32_e32 v92, v92, v116
	v_mul_f32_e32 v93, v93, v117
	v_mul_f32_e32 v94, v94, v118
	v_mul_f32_e32 v95, v95, v119
	v_mul_f32_e32 v100, v100, v110
	v_mul_f32_e32 v101, v101, v110
	v_mul_f32_e32 v102, v102, v110
	v_mul_f32_e32 v103, v103, v110
	v_mul_f32_e32 v104, v104, v110
	v_mul_f32_e32 v105, v105, v110
	v_mul_f32_e32 v106, v106, v110
	v_mul_f32_e32 v107, v107, v110
	v_mul_f32_e32 v100, v100, v24
	v_mul_f32_e32 v101, v101, v25
	v_mul_f32_e32 v102, v102, v26
	v_mul_f32_e32 v103, v103, v27
	v_mul_f32_e32 v104, v104, v28
	v_mul_f32_e32 v105, v105, v29
	v_mul_f32_e32 v106, v106, v30
	v_mul_f32_e32 v107, v107, v31
	v_mul_f32_e32 v112, v88, v52
	v_mul_f32_e32 v113, v89, v54
	v_mul_f32_e32 v114, v90, v56
	v_mul_f32_e32 v115, v91, v58
	v_mul_f32_e32 v116, v92, v60
	v_mul_f32_e32 v117, v93, v62
	v_mul_f32_e32 v118, v94, v64
	v_mul_f32_e32 v119, v95, v66
	v_fmac_f32_e32 v112, v100, v53
	v_fmac_f32_e32 v113, v101, v55
	v_fmac_f32_e32 v114, v102, v57
	v_fmac_f32_e32 v115, v103, v59
	v_fmac_f32_e32 v116, v104, v61
	v_fmac_f32_e32 v117, v105, v63
	v_fmac_f32_e32 v118, v106, v65
	v_fmac_f32_e32 v119, v107, v67
	v_cndmask_b32_e64 v88, v88, v112, s[6:7]
	v_cndmask_b32_e64 v89, v89, v113, s[6:7]
	v_cndmask_b32_e64 v90, v90, v114, s[6:7]
	v_cndmask_b32_e64 v91, v91, v115, s[6:7]
	v_cndmask_b32_e64 v92, v92, v116, s[6:7]
	v_cndmask_b32_e64 v93, v93, v117, s[6:7]
	v_cndmask_b32_e64 v94, v94, v118, s[6:7]
	v_cndmask_b32_e64 v95, v95, v119, s[6:7]
	v_cvt_pk_bf16_f32 v120, v88, v89
	v_cvt_pk_bf16_f32 v121, v90, v91
	v_cvt_pk_bf16_f32 v122, v92, v93
	v_cvt_pk_bf16_f32 v123, v94, v95
	s_mov_b64 exec, s[10:11]
	global_store_dwordx4 v3, v[120:123], s[26:27]
	s_mov_b64 exec, -1
	s_mov_b32 s3, s18
	s_waitcnt vmcnt(1)
; #define UNPK8(v, f) do { f[0] = bflo(v.x); f[1] = bfhi(v.x); f[2] = bflo(v.y); f[3] = bfhi(v.y); f[4] = bflo(v.z); f[5] = bfhi(v.z); f[6] = bflo(v.w); f[7] = bfhi(v.w); } while (0)
; #define PACK8(v, f) do { v.x = pk2(f[0], f[1]); v.y = pk2(f[2], f[3]); v.z = pk2(f[4], f[5]); v.w = pk2(f[6], f[7]); } while (0)
; __global__ void __launch_bounds__(NTHREADS, 2) mega_fwd(Args args) {
;     ...
;         for (int it = gw; it < 2 * T * 2; it += NGW) {
;             const int which = it >= T * 2, j = which ? it - T * 2 : it, row = j >> 1, h = (j & 1) * 4 + (lane >> 4), sub = lane & 15;
;             const bool act = sub < 12;
;             const bf16* src = !which ? QF + (size_t)row * 768 + h * 96 + sub * 8 : (sub < 8 ? KV + (size_t)row * 1024 + h * 128 + sub * 8 : Z + (size_t)row * ZW + 1152 + (sub - 8) * 8);
;             const u32x4 zero4 = {0u, 0u, 0u, 0u};
;             const u32x4 v = act ? *(const u32x4*)src : zero4;
;             float ss = chunk_ss(v); ss += shfl_xor_l(ss, 1, lane); ss += shfl_xor_l(ss, 2, lane); ss += shfl_xor_l(ss, 4, lane); ss += shfl_xor_l(ss, 8, lane);
;             const float r = (1.0f / sqrtf(ss * (1.f / 96.f) + EPS)) * (which ? 1.0f : qsc);
;             const float* gain = which ? INP(13) : INP(12);
;             u32x4 pv;
;             pv.x = __builtin_amdgcn_ds_bpermute((lane ^ 2) << 2, v.x); pv.y = __builtin_amdgcn_ds_bpermute((lane ^ 2) << 2, v.y);
;             pv.z = __builtin_amdgcn_ds_bpermute((lane ^ 2) << 2, v.z); pv.w = __builtin_amdgcn_ds_bpermute((lane ^ 2) << 2, v.w);
;             if (act) {
;                 bf16* dst = (bf16*)(ws + (which ? A_KB : A_QB)) + (size_t)row * 768 + h * 96 + sub * 8;
;                 float f[8]; UNPK8(v, f);
;                 const float* g = gain + sub * 8;
; #pragma unroll
;                 for (int i = 0; i < 8; ++i) f[i] *= r * g[i];
;                 if (sub >= 8) {
;                     float pf_[8]; UNPK8(pv, pf_);
;                     const float* gp = gain + (sub ^ 2) * 8; const float2* cs = rope + (size_t)row * 16 + (sub & 1) * 8;
; #pragma unroll
;                     for (int i = 0; i < 8; ++i) { const float pn = pf_[i] * r * gp[i]; const float2 c = cs[i];
;                         f[i] = (sub < 10) ? (f[i] * c.x - pn * c.y) : (f[i] * c.x + pn * c.y); }
;                 }
;                 u32x4 o; PACK8(o, f); *(u32x4*)dst = o;
.Lp4_q_it1:
	s_add_i32 s18, s3, s28
	s_cmp_ge_i32 s18, 0x10000
	s_cbranch_scc1 .Lp4_q_last1
	s_and_b32 s4, s18, 0xffff
	s_lshr_b32 s5, s4, 1
	s_and_b32 s4, s4, 1
	s_mul_i32 s12, s5, 0x600
	s_mul_i32 s13, s4, 0x300
	s_add_u32 s12, s12, s13
	s_add_u32 s20, s98, 0x11a00000
	s_addc_u32 s21, s99, 0
	s_add_u32 s20, s20, s12
	s_addc_u32 s21, s21, 0
	s_mov_b64 s[22:23], s[20:21]
	s_add_u32 s26, s98, 0x14a00000
	s_addc_u32 s27, s99, 0
	s_add_u32 s26, s26, s12
	s_addc_u32 s27, s27, 0
	s_lshl_b32 s13, s5, 7
	s_add_u32 s24, s98, 0x3d00000
	s_addc_u32 s25, s99, 0
	s_add_u32 s24, s24, s13
	s_addc_u32 s25, s25, 0
	s_mov_b64 exec, s[32:33]
	global_load_dwordx4 v[48:51], v3, s[20:21]
	s_mov_b64 exec, s[8:9]
	global_load_dwordx4 v[48:51], v3, s[22:23]
	s_mov_b64 exec, -1
	global_load_dwordx4 v[52:55], v5, s[24:25] offset:0
	global_load_dwordx4 v[56:59], v5, s[24:25] offset:16
	global_load_dwordx4 v[60:63], v5, s[24:25] offset:32
	global_load_dwordx4 v[64:67], v5, s[24:25] offset:48
	v_lshlrev_b32_e32 v88, 16, v68
	v_and_b32_e32 v89, 0xffff0000, v68
	v_lshlrev_b32_e32 v90, 16, v69
	v_and_b32_e32 v91, 0xffff0000, v69
	v_lshlrev_b32_e32 v92, 16, v70
	v_and_b32_e32 v93, 0xffff0000, v70
	v_lshlrev_b32_e32 v94, 16, v71
	v_and_b32_e32 v95, 0xffff0000, v71
	v_mov_b32_dpp v96, v68 quad_perm:[2,3,0,1] row_mask:0xf bank_mask:0xf
	v_mov_b32_dpp v97, v69 quad_perm:[2,3,0,1] row_mask:0xf bank_mask:0xf
	v_mov_b32_dpp v98, v70 quad_perm:[2,3,0,1] row_mask:0xf bank_mask:0xf
	v_mov_b32_dpp v99, v71 quad_perm:[2,3,0,1] row_mask:0xf bank_mask:0xf
	v_mul_f32_e32 v108, v88, v88
	v_fmac_f32_e32 v108, v89, v89
	v_fmac_f32_e32 v108, v90, v90
	v_fmac_f32_e32 v108, v91, v91
	v_fmac_f32_e32 v108, v92, v92
	v_fmac_f32_e32 v108, v93, v93
	v_fmac_f32_e32 v108, v94, v94
	v_fmac_f32_e32 v108, v95, v95
	s_nop 1
	v_add_f32_dpp v109, v108, v108 quad_perm:[1,0,3,2] row_mask:0xf bank_mask:0xf
	s_nop 1
	v_add_f32_dpp v108, v109, v109 quad_perm:[2,3,0,1] row_mask:0xf bank_mask:0xf
	s_nop 1
	v_add_f32_dpp v109, v108, v108 row_half_mirror row_mask:0xf bank_mask:0xf
	s_nop 1
	v_add_f32_dpp v108, v109, v109 row_mirror row_mask:0xf bank_mask:0xf
	v_lshlrev_b32_e32 v100, 16, v96
	v_and_b32_e32 v101, 0xffff0000, v96
	v_lshlrev_b32_e32 v102, 16, v97
	v_and_b32_e32 v103, 0xffff0000, v97
	v_lshlrev_b32_e32 v104, 16, v98
	v_and_b32_e32 v105, 0xffff0000, v98
	v_lshlrev_b32_e32 v106, 16, v99
	v_and_b32_e32 v107, 0xffff0000, v99
	v_fmamk_f32 v109, v108, 0x3c2aaaab, v14
	v_rsq_f32_e32 v110, v109
	s_nop 0
	v_mul_f32_e32 v111, v109, v110
	v_mul_f32_e32 v111, v111, v110
	v_fma_f32 v111, v111, -0.5, v15
	v_mul_f32_e32 v110, v110, v111
	v_mul_f32_e32 v110, 0x3e16c740, v110
	v_mul_f32_e32 v112, v110, v16
	v_mul_f32_e32 v113, v110, v17
	v_mul_f32_e32 v114, v110, v18
	v_mul_f32_e32 v115, v110, v19
	v_mul_f32_e32 v116, v110, v20
	v_mul_f32_e32 v117, v110, v21
	v_mul_f32_e32 v118, v110, v22
	v_mul_f32_e32 v119, v110, v23
	v_mul_f32_e32 v88, v88, v112
	v_mul_f32_e32 v89, v89, v113
	v_mul_f32_e32 v90, v90, v114
	v_mul_f32_e32 v91, v91, v115
	v_mul_f32_e32 v92, v92, v116
	v_mul_f32_e32 v93, v93, v117
	v_mul_f32_e32 v94, v94, v118
	v_mul_f32_e32 v95, v95, v119
	v_mul_f32_e32 v100, v100, v110
	v_mul_f32_e32 v101, v101, v110
	v_mul_f32_e32 v102, v102, v110
	v_mul_f32_e32 v103, v103, v110
	v_mul_f32_e32 v104, v104, v110
	v_mul_f32_e32 v105, v105, v110
	v_mul_f32_e32 v106, v106, v110
	v_mul_f32_e32 v107, v107, v110
	v_mul_f32_e32 v100, v100, v24
	v_mul_f32_e32 v101, v101, v25
	v_mul_f32_e32 v102, v102, v26
	v_mul_f32_e32 v103, v103, v27
	v_mul_f32_e32 v104, v104, v28
	v_mul_f32_e32 v105, v105, v29
	v_mul_f32_e32 v106, v106, v30
	v_mul_f32_e32 v107, v107, v31
	v_mul_f32_e32 v112, v88, v72
	v_mul_f32_e32 v113, v89, v74
	v_mul_f32_e32 v114, v90, v76
	v_mul_f32_e32 v115, v91, v78
	v_mul_f32_e32 v116, v92, v80
	v_mul_f32_e32 v117, v93, v82
	v_mul_f32_e32 v118, v94, v84
	v_mul_f32_e32 v119, v95, v86
	v_fmac_f32_e32 v112, v100, v73
	v_fmac_f32_e32 v113, v101, v75
	v_fmac_f32_e32 v114, v102, v77
	v_fmac_f32_e32 v115, v103, v79
	v_fmac_f32_e32 v116, v104, v81
	v_fmac_f32_e32 v117, v105, v83
	v_fmac_f32_e32 v118, v106, v85
	v_fmac_f32_e32 v119, v107, v87
	v_cndmask_b32_e64 v88, v88, v112, s[6:7]
	v_cndmask_b32_e64 v89, v89, v113, s[6:7]
	v_cndmask_b32_e64 v90, v90, v114, s[6:7]
	v_cndmask_b32_e64 v91, v91, v115, s[6:7]
	v_cndmask_b32_e64 v92, v92, v116, s[6:7]
	v_cndmask_b32_e64 v93, v93, v117, s[6:7]
	v_cndmask_b32_e64 v94, v94, v118, s[6:7]
	v_cndmask_b32_e64 v95, v95, v119, s[6:7]
	v_cvt_pk_bf16_f32 v120, v88, v89
	v_cvt_pk_bf16_f32 v121, v90, v91
	v_cvt_pk_bf16_f32 v122, v92, v93
	v_cvt_pk_bf16_f32 v123, v94, v95
	s_mov_b64 exec, s[10:11]
	global_store_dwordx4 v3, v[120:123], s[30:31]
	s_mov_b64 exec, -1
	s_mov_b32 s3, s18
	s_waitcnt vmcnt(1)
	s_branch .Lp4_q_it0
; #define UNPK8(v, f) do { f[0] = bflo(v.x); f[1] = bfhi(v.x); f[2] = bflo(v.y); f[3] = bfhi(v.y); f[4] = bflo(v.z); f[5] = bfhi(v.z); f[6] = bflo(v.w); f[7] = bfhi(v.w); } while (0)
; #define PACK8(v, f) do { v.x = pk2(f[0], f[1]); v.y = pk2(f[2], f[3]); v.z = pk2(f[4], f[5]); v.w = pk2(f[6], f[7]); } while (0)
; __global__ void __launch_bounds__(NTHREADS, 2) mega_fwd(Args args) {
;     ...
;         for (int it = gw; it < 2 * T * 2; it += NGW) {
;             const int which = it >= T * 2, j = which ? it - T * 2 : it, row = j >> 1, h = (j & 1) * 4 + (lane >> 4), sub = lane & 15;
;             const bool act = sub < 12;
;             const bf16* src = !which ? QF + (size_t)row * 768 + h * 96 + sub * 8 : (sub < 8 ? KV + (size_t)row * 1024 + h * 128 + sub * 8 : Z + (size_t)row * ZW + 1152 + (sub - 8) * 8);
;             const u32x4 zero4 = {0u, 0u, 0u, 0u};
;             const u32x4 v = act ? *(const u32x4*)src : zero4;
;             float ss = chunk_ss(v); ss += shfl_xor_l(ss, 1, lane); ss += shfl_xor_l(ss, 2, lane); ss += shfl_xor_l(ss, 4, lane); ss += shfl_xor_l(ss, 8, lane);
;             const float r = (1.0f / sqrtf(ss * (1.f / 96.f) + EPS)) * (which ? 1.0f : qsc);
;             const float* gain = which ? INP(13) : INP(12);
;             u32x4 pv;
;             pv.x = __builtin_amdgcn_ds_bpermute((lane ^ 2) << 2, v.x); pv.y = __builtin_amdgcn_ds_bpermute((lane ^ 2) << 2, v.y);
;             pv.z = __builtin_amdgcn_ds_bpermute((lane ^ 2) << 2, v.z); pv.w = __builtin_amdgcn_ds_bpermute((lane ^ 2) << 2, v.w);
;             if (act) {
;                 bf16* dst = (bf16*)(ws + (which ? A_KB : A_QB)) + (size_t)row * 768 + h * 96 + sub * 8;
;                 float f[8]; UNPK8(v, f);
;                 const float* g = gain + sub * 8;
; #pragma unroll
;                 for (int i = 0; i < 8; ++i) f[i] *= r * g[i];
;                 if (sub >= 8) {
;                     float pf_[8]; UNPK8(pv, pf_);
;                     const float* gp = gain + (sub ^ 2) * 8; const float2* cs = rope + (size_t)row * 16 + (sub & 1) * 8;
; #pragma unroll
;                     for (int i = 0; i < 8; ++i) { const float pn = pf_[i] * r * gp[i]; const float2 c = cs[i];
;                         f[i] = (sub < 10) ? (f[i] * c.x - pn * c.y) : (f[i] * c.x + pn * c.y); }
;                 }
;                 u32x4 o; PACK8(o, f); *(u32x4*)dst = o;
.Lp4_q_last0:
	v_lshlrev_b32_e32 v88, 16, v48
	v_and_b32_e32 v89, 0xffff0000, v48
	v_lshlrev_b32_e32 v90, 16, v49
	v_and_b32_e32 v91, 0xffff0000, v49
	v_lshlrev_b32_e32 v92, 16, v50
	v_and_b32_e32 v93, 0xffff0000, v50
	v_lshlrev_b32_e32 v94, 16, v51
	v_and_b32_e32 v95, 0xffff0000, v51
	v_mov_b32_dpp v96, v48 quad_perm:[2,3,0,1] row_mask:0xf bank_mask:0xf
	v_mov_b32_dpp v97, v49 quad_perm:[2,3,0,1] row_mask:0xf bank_mask:0xf
	v_mov_b32_dpp v98, v50 quad_perm:[2,3,0,1] row_mask:0xf bank_mask:0xf
	v_mov_b32_dpp v99, v51 quad_perm:[2,3,0,1] row_mask:0xf bank_mask:0xf
	v_mul_f32_e32 v108, v88, v88
	v_fmac_f32_e32 v108, v89, v89
	v_fmac_f32_e32 v108, v90, v90
	v_fmac_f32_e32 v108, v91, v91
	v_fmac_f32_e32 v108, v92, v92
	v_fmac_f32_e32 v108, v93, v93
	v_fmac_f32_e32 v108, v94, v94
	v_fmac_f32_e32 v108, v95, v95
	s_nop 1
	v_add_f32_dpp v109, v108, v108 quad_perm:[1,0,3,2] row_mask:0xf bank_mask:0xf
	s_nop 1
	v_add_f32_dpp v108, v109, v109 quad_perm:[2,3,0,1] row_mask:0xf bank_mask:0xf
	s_nop 1
	v_add_f32_dpp v109, v108, v108 row_half_mirror row_mask:0xf bank_mask:0xf
	s_nop 1
	v_add_f32_dpp v108, v109, v109 row_mirror row_mask:0xf bank_mask:0xf
	v_lshlrev_b32_e32 v100, 16, v96
	v_and_b32_e32 v101, 0xffff0000, v96
	v_lshlrev_b32_e32 v102, 16, v97
	v_and_b32_e32 v103, 0xffff0000, v97
	v_lshlrev_b32_e32 v104, 16, v98
	v_and_b32_e32 v105, 0xffff0000, v98
	v_lshlrev_b32_e32 v106, 16, v99
	v_and_b32_e32 v107, 0xffff0000, v99
	v_fmamk_f32 v109, v108, 0x3c2aaaab, v14
	v_rsq_f32_e32 v110, v109
	s_nop 0
	v_mul_f32_e32 v111, v109, v110
	v_mul_f32_e32 v111, v111, v110
	v_fma_f32 v111, v111, -0.5, v15
	v_mul_f32_e32 v110, v110, v111
	v_mul_f32_e32 v110, 0x3e16c740, v110
	v_mul_f32_e32 v112, v110, v16
	v_mul_f32_e32 v113, v110, v17
	v_mul_f32_e32 v114, v110, v18
	v_mul_f32_e32 v115, v110, v19
	v_mul_f32_e32 v116, v110, v20
	v_mul_f32_e32 v117, v110, v21
	v_mul_f32_e32 v118, v110, v22
	v_mul_f32_e32 v119, v110, v23
	v_mul_f32_e32 v88, v88, v112
	v_mul_f32_e32 v89, v89, v113
	v_mul_f32_e32 v90, v90, v114
	v_mul_f32_e32 v91, v91, v115
	v_mul_f32_e32 v92, v92, v116
	v_mul_f32_e32 v93, v93, v117
	v_mul_f32_e32 v94, v94, v118
	v_mul_f32_e32 v95, v95, v119
	v_mul_f32_e32 v100, v100, v110
	v_mul_f32_e32 v101, v101, v110
	v_mul_f32_e32 v102, v102, v110
	v_mul_f32_e32 v103, v103, v110
	v_mul_f32_e32 v104, v104, v110
	v_mul_f32_e32 v105, v105, v110
	v_mul_f32_e32 v106, v106, v110
	v_mul_f32_e32 v107, v107, v110
	v_mul_f32_e32 v100, v100, v24
	v_mul_f32_e32 v101, v101, v25
	v_mul_f32_e32 v102, v102, v26
	v_mul_f32_e32 v103, v103, v27
	v_mul_f32_e32 v104, v104, v28
	v_mul_f32_e32 v105, v105, v29
	v_mul_f32_e32 v106, v106, v30
	v_mul_f32_e32 v107, v107, v31
	v_mul_f32_e32 v112, v88, v52
	v_mul_f32_e32 v113, v89, v54
	v_mul_f32_e32 v114, v90, v56
	v_mul_f32_e32 v115, v91, v58
	v_mul_f32_e32 v116, v92, v60
	v_mul_f32_e32 v117, v93, v62
	v_mul_f32_e32 v118, v94, v64
	v_mul_f32_e32 v119, v95, v66
	v_fmac_f32_e32 v112, v100, v53
	v_fmac_f32_e32 v113, v101, v55
	v_fmac_f32_e32 v114, v102, v57
	v_fmac_f32_e32 v115, v103, v59
	v_fmac_f32_e32 v116, v104, v61
	v_fmac_f32_e32 v117, v105, v63
	v_fmac_f32_e32 v118, v106, v65
	v_fmac_f32_e32 v119, v107, v67
	v_cndmask_b32_e64 v88, v88, v112, s[6:7]
	v_cndmask_b32_e64 v89, v89, v113, s[6:7]
	v_cndmask_b32_e64 v90, v90, v114, s[6:7]
	v_cndmask_b32_e64 v91, v91, v115, s[6:7]
	v_cndmask_b32_e64 v92, v92, v116, s[6:7]
	v_cndmask_b32_e64 v93, v93, v117, s[6:7]
	v_cndmask_b32_e64 v94, v94, v118, s[6:7]
	v_cndmask_b32_e64 v95, v95, v119, s[6:7]
	v_cvt_pk_bf16_f32 v120, v88, v89
	v_cvt_pk_bf16_f32 v121, v90, v91
	v_cvt_pk_bf16_f32 v122, v92, v93
	v_cvt_pk_bf16_f32 v123, v94, v95
	s_mov_b64 exec, s[10:11]
	global_store_dwordx4 v3, v[120:123], s[26:27]
	s_mov_b64 exec, -1
	s_mov_b32 s3, s18
	s_branch .Lp4_q_done
.Lp4_q_last1:
	v_lshlrev_b32_e32 v88, 16, v68
	v_and_b32_e32 v89, 0xffff0000, v68
	v_lshlrev_b32_e32 v90, 16, v69
	v_and_b32_e32 v91, 0xffff0000, v69
	v_lshlrev_b32_e32 v92, 16, v70
	v_and_b32_e32 v93, 0xffff0000, v70
	v_lshlrev_b32_e32 v94, 16, v71
	v_and_b32_e32 v95, 0xffff0000, v71
	v_mov_b32_dpp v96, v68 quad_perm:[2,3,0,1] row_mask:0xf bank_mask:0xf
	v_mov_b32_dpp v97, v69 quad_perm:[2,3,0,1] row_mask:0xf bank_mask:0xf
	v_mov_b32_dpp v98, v70 quad_perm:[2,3,0,1] row_mask:0xf bank_mask:0xf
	v_mov_b32_dpp v99, v71 quad_perm:[2,3,0,1] row_mask:0xf bank_mask:0xf
	v_mul_f32_e32 v108, v88, v88
	v_fmac_f32_e32 v108, v89, v89
	v_fmac_f32_e32 v108, v90, v90
	v_fmac_f32_e32 v108, v91, v91
	v_fmac_f32_e32 v108, v92, v92
	v_fmac_f32_e32 v108, v93, v93
	v_fmac_f32_e32 v108, v94, v94
	v_fmac_f32_e32 v108, v95, v95
	s_nop 1
	v_add_f32_dpp v109, v108, v108 quad_perm:[1,0,3,2] row_mask:0xf bank_mask:0xf
	s_nop 1
	v_add_f32_dpp v108, v109, v109 quad_perm:[2,3,0,1] row_mask:0xf bank_mask:0xf
	s_nop 1
	v_add_f32_dpp v109, v108, v108 row_half_mirror row_mask:0xf bank_mask:0xf
	s_nop 1
	v_add_f32_dpp v108, v109, v109 row_mirror row_mask:0xf bank_mask:0xf
	v_lshlrev_b32_e32 v100, 16, v96
	v_and_b32_e32 v101, 0xffff0000, v96
	v_lshlrev_b32_e32 v102, 16, v97
	v_and_b32_e32 v103, 0xffff0000, v97
	v_lshlrev_b32_e32 v104, 16, v98
	v_and_b32_e32 v105, 0xffff0000, v98
	v_lshlrev_b32_e32 v106, 16, v99
	v_and_b32_e32 v107, 0xffff0000, v99
	v_fmamk_f32 v109, v108, 0x3c2aaaab, v14
	v_rsq_f32_e32 v110, v109
	s_nop 0
	v_mul_f32_e32 v111, v109, v110
	v_mul_f32_e32 v111, v111, v110
	v_fma_f32 v111, v111, -0.5, v15
	v_mul_f32_e32 v110, v110, v111
	v_mul_f32_e32 v110, 0x3e16c740, v110
	v_mul_f32_e32 v112, v110, v16
	v_mul_f32_e32 v113, v110, v17
	v_mul_f32_e32 v114, v110, v18
	v_mul_f32_e32 v115, v110, v19
	v_mul_f32_e32 v116, v110, v20
	v_mul_f32_e32 v117, v110, v21
; #define UNPK8(v, f) do { f[0] = bflo(v.x); f[1] = bfhi(v.x); f[2] = bflo(v.y); f[3] = bfhi(v.y); f[4] = bflo(v.z); f[5] = bfhi(v.z); f[6] = bflo(v.w); f[7] = bfhi(v.w); } while (0)
; #define PACK8(v, f) do { v.x = pk2(f[0], f[1]); v.y = pk2(f[2], f[3]); v.z = pk2(f[4], f[5]); v.w = pk2(f[6], f[7]); } while (0)
; __global__ void __launch_bounds__(NTHREADS, 2) mega_fwd(Args args) {
;     ...
;         for (int it = gw; it < 2 * T * 2; it += NGW) {
;             const int which = it >= T * 2, j = which ? it - T * 2 : it, row = j >> 1, h = (j & 1) * 4 + (lane >> 4), sub = lane & 15;
;             const bool act = sub < 12;
;             const bf16* src = !which ? QF + (size_t)row * 768 + h * 96 + sub * 8 : (sub < 8 ? KV + (size_t)row * 1024 + h * 128 + sub * 8 : Z + (size_t)row * ZW + 1152 + (sub - 8) * 8);
;             const u32x4 zero4 = {0u, 0u, 0u, 0u};
;             const u32x4 v = act ? *(const u32x4*)src : zero4;
;             float ss = chunk_ss(v); ss += shfl_xor_l(ss, 1, lane); ss += shfl_xor_l(ss, 2, lane); ss += shfl_xor_l(ss, 4, lane); ss += shfl_xor_l(ss, 8, lane);
;             const float r = (1.0f / sqrtf(ss * (1.f / 96.f) + EPS)) * (which ? 1.0f : qsc);
;             const float* gain = which ? INP(13) : INP(12);
;             u32x4 pv;
;             pv.x = __builtin_amdgcn_ds_bpermute((lane ^ 2) << 2, v.x); pv.y = __builtin_amdgcn_ds_bpermute((lane ^ 2) << 2, v.y);
;             pv.z = __builtin_amdgcn_ds_bpermute((lane ^ 2) << 2, v.z); pv.w = __builtin_amdgcn_ds_bpermute((lane ^ 2) << 2, v.w);
;             if (act) {
;                 bf16* dst = (bf16*)(ws + (which ? A_KB : A_QB)) + (size_t)row * 768 + h * 96 + sub * 8;
;                 float f[8]; UNPK8(v, f);
;                 const float* g = gain + sub * 8;
; #pragma unroll
;                 for (int i = 0; i < 8; ++i) f[i] *= r * g[i];
;                 if (sub >= 8) {
;                     float pf_[8]; UNPK8(pv, pf_);
;                     const float* gp = gain + (sub ^ 2) * 8; const float2* cs = rope + (size_t)row * 16 + (sub & 1) * 8;
; #pragma unroll
;                     for (int i = 0; i < 8; ++i) { const float pn = pf_[i] * r * gp[i]; const float2 c = cs[i];
;                         f[i] = (sub < 10) ? (f[i] * c.x - pn * c.y) : (f[i] * c.x + pn * c.y); }
;                 }
;                 u32x4 o; PACK8(o, f); *(u32x4*)dst = o;
	v_mul_f32_e32 v118, v110, v22
	v_mul_f32_e32 v119, v110, v23
	v_mul_f32_e32 v88, v88, v112
	v_mul_f32_e32 v89, v89, v113
	v_mul_f32_e32 v90, v90, v114
	v_mul_f32_e32 v91, v91, v115
	v_mul_f32_e32 v92, v92, v116
	v_mul_f32_e32 v93, v93, v117
	v_mul_f32_e32 v94, v94, v118
	v_mul_f32_e32 v95, v95, v119
	v_mul_f32_e32 v100, v100, v110
	v_mul_f32_e32 v101, v101, v110
	v_mul_f32_e32 v102, v102, v110
	v_mul_f32_e32 v103, v103, v110
	v_mul_f32_e32 v104, v104, v110
	v_mul_f32_e32 v105, v105, v110
	v_mul_f32_e32 v106, v106, v110
	v_mul_f32_e32 v107, v107, v110
	v_mul_f32_e32 v100, v100, v24
	v_mul_f32_e32 v101, v101, v25
	v_mul_f32_e32 v102, v102, v26
	v_mul_f32_e32 v103, v103, v27
	v_mul_f32_e32 v104, v104, v28
	v_mul_f32_e32 v105, v105, v29
	v_mul_f32_e32 v106, v106, v30
	v_mul_f32_e32 v107, v107, v31
	v_mul_f32_e32 v112, v88, v72
	v_mul_f32_e32 v113, v89, v74
	v_mul_f32_e32 v114, v90, v76
	v_mul_f32_e32 v115, v91, v78
	v_mul_f32_e32 v116, v92, v80
	v_mul_f32_e32 v117, v93, v82
	v_mul_f32_e32 v118, v94, v84
	v_mul_f32_e32 v119, v95, v86
	v_fmac_f32_e32 v112, v100, v73
	v_fmac_f32_e32 v113, v101, v75
	v_fmac_f32_e32 v114, v102, v77
	v_fmac_f32_e32 v115, v103, v79
	v_fmac_f32_e32 v116, v104, v81
	v_fmac_f32_e32 v117, v105, v83
	v_fmac_f32_e32 v118, v106, v85
	v_fmac_f32_e32 v119, v107, v87
	v_cndmask_b32_e64 v88, v88, v112, s[6:7]
	v_cndmask_b32_e64 v89, v89, v113, s[6:7]
	v_cndmask_b32_e64 v90, v90, v114, s[6:7]
	v_cndmask_b32_e64 v91, v91, v115, s[6:7]
	v_cndmask_b32_e64 v92, v92, v116, s[6:7]
	v_cndmask_b32_e64 v93, v93, v117, s[6:7]
	v_cndmask_b32_e64 v94, v94, v118, s[6:7]
	v_cndmask_b32_e64 v95, v95, v119, s[6:7]
	v_cvt_pk_bf16_f32 v120, v88, v89
	v_cvt_pk_bf16_f32 v121, v90, v91
	v_cvt_pk_bf16_f32 v122, v92, v93
	v_cvt_pk_bf16_f32 v123, v94, v95
	s_mov_b64 exec, s[10:11]
	global_store_dwordx4 v3, v[120:123], s[30:31]
	s_mov_b64 exec, -1
	s_mov_b32 s3, s18
	s_branch .Lp4_q_done
.Lp4_q_done:
	s_cmp_ge_i32 s3, 0x20000
	s_cbranch_scc1 .Lp4_k_done
	s_and_b32 s4, s3, 0xffff
	s_lshr_b32 s5, s4, 1
	s_and_b32 s4, s4, 1
	s_mul_i32 s12, s5, 0x600
	s_mul_i32 s13, s4, 0x300
	s_add_u32 s12, s12, s13
	s_lshl_b32 s13, s5, 11
	s_lshl_b32 s19, s4, 10
	s_add_u32 s13, s13, s19
	s_add_u32 s20, s98, 0x4200000
	s_addc_u32 s21, s99, 0
	s_add_u32 s20, s20, s13
	s_addc_u32 s21, s21, 0
	s_mul_i32 s13, s5, 0xa00
	s_add_u32 s22, s98, 0x8200000
	s_addc_u32 s23, s99, 0
	s_add_u32 s22, s22, s13
	s_addc_u32 s23, s23, 0
	s_add_u32 s26, s98, 0x17a00000
	s_addc_u32 s27, s99, 0
	s_add_u32 s26, s26, s12
	s_addc_u32 s27, s27, 0
	s_lshl_b32 s13, s5, 7
	s_add_u32 s24, s98, 0x3d00000
	s_addc_u32 s25, s99, 0
	s_add_u32 s24, s24, s13
	s_addc_u32 s25, s25, 0
	s_mov_b64 exec, s[32:33]
	global_load_dwordx4 v[48:51], v4, s[20:21]
	s_mov_b64 exec, s[8:9]
	global_load_dwordx4 v[48:51], v13, s[22:23]
	s_mov_b64 exec, -1
	global_load_dwordx4 v[52:55], v5, s[24:25] offset:0
	global_load_dwordx4 v[56:59], v5, s[24:25] offset:16
	global_load_dwordx4 v[60:63], v5, s[24:25] offset:32
	global_load_dwordx4 v[64:67], v5, s[24:25] offset:48
	s_waitcnt vmcnt(0)
.Lp4_k_it0:
	s_add_i32 s18, s3, s28
	s_cmp_ge_i32 s18, 0x20000
	s_cbranch_scc1 .Lp4_k_last0
	s_and_b32 s4, s18, 0xffff
	s_lshr_b32 s5, s4, 1
	s_and_b32 s4, s4, 1
	s_mul_i32 s12, s5, 0x600
	s_mul_i32 s13, s4, 0x300
	s_add_u32 s12, s12, s13
	s_lshl_b32 s13, s5, 11
	s_lshl_b32 s19, s4, 10
	s_add_u32 s13, s13, s19
	s_add_u32 s20, s98, 0x4200000
	s_addc_u32 s21, s99, 0
	s_add_u32 s20, s20, s13
	s_addc_u32 s21, s21, 0
	s_mul_i32 s13, s5, 0xa00
	s_add_u32 s22, s98, 0x8200000
	s_addc_u32 s23, s99, 0
	s_add_u32 s22, s22, s13
	s_addc_u32 s23, s23, 0
	s_add_u32 s30, s98, 0x17a00000
	s_addc_u32 s31, s99, 0
	s_add_u32 s30, s30, s12
	s_addc_u32 s31, s31, 0
	s_lshl_b32 s13, s5, 7
	s_add_u32 s24, s98, 0x3d00000
	s_addc_u32 s25, s99, 0
	s_add_u32 s24, s24, s13
	s_addc_u32 s25, s25, 0
	s_mov_b64 exec, s[32:33]
	global_load_dwordx4 v[68:71], v4, s[20:21]
	s_mov_b64 exec, s[8:9]
	global_load_dwordx4 v[68:71], v13, s[22:23]
	s_mov_b64 exec, -1
	global_load_dwordx4 v[72:75], v5, s[24:25] offset:0
	global_load_dwordx4 v[76:79], v5, s[24:25] offset:16
	global_load_dwordx4 v[80:83], v5, s[24:25] offset:32
	global_load_dwordx4 v[84:87], v5, s[24:25] offset:48
	v_lshlrev_b32_e32 v88, 16, v48
	v_and_b32_e32 v89, 0xffff0000, v48
	v_lshlrev_b32_e32 v90, 16, v49
	v_and_b32_e32 v91, 0xffff0000, v49
	v_lshlrev_b32_e32 v92, 16, v50
	v_and_b32_e32 v93, 0xffff0000, v50
	v_lshlrev_b32_e32 v94, 16, v51
	v_and_b32_e32 v95, 0xffff0000, v51
	v_mov_b32_dpp v96, v48 quad_perm:[2,3,0,1] row_mask:0xf bank_mask:0xf
	v_mov_b32_dpp v97, v49 quad_perm:[2,3,0,1] row_mask:0xf bank_mask:0xf
	v_mov_b32_dpp v98, v50 quad_perm:[2,3,0,1] row_mask:0xf bank_mask:0xf
	v_mov_b32_dpp v99, v51 quad_perm:[2,3,0,1] row_mask:0xf bank_mask:0xf
	v_mul_f32_e32 v108, v88, v88
	v_fmac_f32_e32 v108, v89, v89
	v_fmac_f32_e32 v108, v90, v90
	v_fmac_f32_e32 v108, v91, v91
	v_fmac_f32_e32 v108, v92, v92
	v_fmac_f32_e32 v108, v93, v93
	v_fmac_f32_e32 v108, v94, v94
	v_fmac_f32_e32 v108, v95, v95
	s_nop 1
	v_add_f32_dpp v109, v108, v108 quad_perm:[1,0,3,2] row_mask:0xf bank_mask:0xf
	s_nop 1
	v_add_f32_dpp v108, v109, v109 quad_perm:[2,3,0,1] row_mask:0xf bank_mask:0xf
	s_nop 1
	v_add_f32_dpp v109, v108, v108 row_half_mirror row_mask:0xf bank_mask:0xf
	s_nop 1
	v_add_f32_dpp v108, v109, v109 row_mirror row_mask:0xf bank_mask:0xf
	v_lshlrev_b32_e32 v100, 16, v96
	v_and_b32_e32 v101, 0xffff0000, v96
	v_lshlrev_b32_e32 v102, 16, v97
	v_and_b32_e32 v103, 0xffff0000, v97
	v_lshlrev_b32_e32 v104, 16, v98
	v_and_b32_e32 v105, 0xffff0000, v98
	v_lshlrev_b32_e32 v106, 16, v99
	v_and_b32_e32 v107, 0xffff0000, v99
; #define UNPK8(v, f) do { f[0] = bflo(v.x); f[1] = bfhi(v.x); f[2] = bflo(v.y); f[3] = bfhi(v.y); f[4] = bflo(v.z); f[5] = bfhi(v.z); f[6] = bflo(v.w); f[7] = bfhi(v.w); } while (0)
; #define PACK8(v, f) do { v.x = pk2(f[0], f[1]); v.y = pk2(f[2], f[3]); v.z = pk2(f[4], f[5]); v.w = pk2(f[6], f[7]); } while (0)
; __global__ void __launch_bounds__(NTHREADS, 2) mega_fwd(Args args) {
;     ...
;         for (int it = gw; it < 2 * T * 2; it += NGW) {
;             const int which = it >= T * 2, j = which ? it - T * 2 : it, row = j >> 1, h = (j & 1) * 4 + (lane >> 4), sub = lane & 15;
;             const bool act = sub < 12;
;             const bf16* src = !which ? QF + (size_t)row * 768 + h * 96 + sub * 8 : (sub < 8 ? KV + (size_t)row * 1024 + h * 128 + sub * 8 : Z + (size_t)row * ZW + 1152 + (sub - 8) * 8);
;             const u32x4 zero4 = {0u, 0u, 0u, 0u};
;             const u32x4 v = act ? *(const u32x4*)src : zero4;
;             float ss = chunk_ss(v); ss += shfl_xor_l(ss, 1, lane); ss += shfl_xor_l(ss, 2, lane); ss += shfl_xor_l(ss, 4, lane); ss += shfl_xor_l(ss, 8, lane);
;             const float r = (1.0f / sqrtf(ss * (1.f / 96.f) + EPS)) * (which ? 1.0f : qsc);
;             const float* gain = which ? INP(13) : INP(12);
;             u32x4 pv;
;             pv.x = __builtin_amdgcn_ds_bpermute((lane ^ 2) << 2, v.x); pv.y = __builtin_amdgcn_ds_bpermute((lane ^ 2) << 2, v.y);
;             pv.z = __builtin_amdgcn_ds_bpermute((lane ^ 2) << 2, v.z); pv.w = __builtin_amdgcn_ds_bpermute((lane ^ 2) << 2, v.w);
;             if (act) {
;                 bf16* dst = (bf16*)(ws + (which ? A_KB : A_QB)) + (size_t)row * 768 + h * 96 + sub * 8;
;                 float f[8]; UNPK8(v, f);
;                 const float* g = gain + sub * 8;
; #pragma unroll
;                 for (int i = 0; i < 8; ++i) f[i] *= r * g[i];
;                 if (sub >= 8) {
;                     float pf_[8]; UNPK8(pv, pf_);
;                     const float* gp = gain + (sub ^ 2) * 8; const float2* cs = rope + (size_t)row * 16 + (sub & 1) * 8;
; #pragma unroll
;                     for (int i = 0; i < 8; ++i) { const float pn = pf_[i] * r * gp[i]; const float2 c = cs[i];
;                         f[i] = (sub < 10) ? (f[i] * c.x - pn * c.y) : (f[i] * c.x + pn * c.y); }
;                 }
;                 u32x4 o; PACK8(o, f); *(u32x4*)dst = o;
	v_fmamk_f32 v109, v108, 0x3c2aaaab, v14
	v_rsq_f32_e32 v110, v109
	s_nop 0
	v_mul_f32_e32 v111, v109, v110
	v_mul_f32_e32 v111, v111, v110
	v_fma_f32 v111, v111, -0.5, v15
	v_mul_f32_e32 v110, v110, v111
	v_mul_f32_e32 v112, v110, v32
	v_mul_f32_e32 v113, v110, v33
	v_mul_f32_e32 v114, v110, v34
	v_mul_f32_e32 v115, v110, v35
	v_mul_f32_e32 v116, v110, v36
	v_mul_f32_e32 v117, v110, v37
	v_mul_f32_e32 v118, v110, v38
	v_mul_f32_e32 v119, v110, v39
	v_mul_f32_e32 v88, v88, v112
	v_mul_f32_e32 v89, v89, v113
	v_mul_f32_e32 v90, v90, v114
	v_mul_f32_e32 v91, v91, v115
	v_mul_f32_e32 v92, v92, v116
	v_mul_f32_e32 v93, v93, v117
	v_mul_f32_e32 v94, v94, v118
	v_mul_f32_e32 v95, v95, v119
	v_mul_f32_e32 v100, v100, v110
	v_mul_f32_e32 v101, v101, v110
	v_mul_f32_e32 v102, v102, v110
	v_mul_f32_e32 v103, v103, v110
	v_mul_f32_e32 v104, v104, v110
	v_mul_f32_e32 v105, v105, v110
	v_mul_f32_e32 v106, v106, v110
	v_mul_f32_e32 v107, v107, v110
	v_mul_f32_e32 v100, v100, v40
	v_mul_f32_e32 v101, v101, v41
	v_mul_f32_e32 v102, v102, v42
	v_mul_f32_e32 v103, v103, v43
	v_mul_f32_e32 v104, v104, v44
	v_mul_f32_e32 v105, v105, v45
	v_mul_f32_e32 v106, v106, v46
	v_mul_f32_e32 v107, v107, v47
	v_mul_f32_e32 v112, v88, v52
	v_mul_f32_e32 v113, v89, v54
	v_mul_f32_e32 v114, v90, v56
	v_mul_f32_e32 v115, v91, v58
	v_mul_f32_e32 v116, v92, v60
	v_mul_f32_e32 v117, v93, v62
	v_mul_f32_e32 v118, v94, v64
	v_mul_f32_e32 v119, v95, v66
	v_fmac_f32_e32 v112, v100, v53
	v_fmac_f32_e32 v113, v101, v55
	v_fmac_f32_e32 v114, v102, v57
	v_fmac_f32_e32 v115, v103, v59
	v_fmac_f32_e32 v116, v104, v61
	v_fmac_f32_e32 v117, v105, v63
	v_fmac_f32_e32 v118, v106, v65
	v_fmac_f32_e32 v119, v107, v67
	v_cndmask_b32_e64 v88, v88, v112, s[6:7]
	v_cndmask_b32_e64 v89, v89, v113, s[6:7]
	v_cndmask_b32_e64 v90, v90, v114, s[6:7]
	v_cndmask_b32_e64 v91, v91, v115, s[6:7]
	v_cndmask_b32_e64 v92, v92, v116, s[6:7]
	v_cndmask_b32_e64 v93, v93, v117, s[6:7]
	v_cndmask_b32_e64 v94, v94, v118, s[6:7]
	v_cndmask_b32_e64 v95, v95, v119, s[6:7]
	v_cvt_pk_bf16_f32 v120, v88, v89
	v_cvt_pk_bf16_f32 v121, v90, v91
	v_cvt_pk_bf16_f32 v122, v92, v93
	v_cvt_pk_bf16_f32 v123, v94, v95
	s_mov_b64 exec, s[10:11]
	global_store_dwordx4 v3, v[120:123], s[26:27]
	s_mov_b64 exec, -1
	s_mov_b32 s3, s18
	s_waitcnt vmcnt(1)
.Lp4_k_it1:
	s_add_i32 s18, s3, s28
	s_cmp_ge_i32 s18, 0x20000
	s_cbranch_scc1 .Lp4_k_last1
	s_and_b32 s4, s18, 0xffff
	s_lshr_b32 s5, s4, 1
	s_and_b32 s4, s4, 1
	s_mul_i32 s12, s5, 0x600
	s_mul_i32 s13, s4, 0x300
	s_add_u32 s12, s12, s13
	s_lshl_b32 s13, s5, 11
	s_lshl_b32 s19, s4, 10
	s_add_u32 s13, s13, s19
	s_add_u32 s20, s98, 0x4200000
	s_addc_u32 s21, s99, 0
	s_add_u32 s20, s20, s13
	s_addc_u32 s21, s21, 0
	s_mul_i32 s13, s5, 0xa00
	s_add_u32 s22, s98, 0x8200000
	s_addc_u32 s23, s99, 0
	s_add_u32 s22, s22, s13
	s_addc_u32 s23, s23, 0
	s_add_u32 s26, s98, 0x17a00000
	s_addc_u32 s27, s99, 0
	s_add_u32 s26, s26, s12
	s_addc_u32 s27, s27, 0
	s_lshl_b32 s13, s5, 7
	s_add_u32 s24, s98, 0x3d00000
	s_addc_u32 s25, s99, 0
	s_add_u32 s24, s24, s13
	s_addc_u32 s25, s25, 0
	s_mov_b64 exec, s[32:33]
	global_load_dwordx4 v[48:51], v4, s[20:21]
	s_mov_b64 exec, s[8:9]
	global_load_dwordx4 v[48:51], v13, s[22:23]
	s_mov_b64 exec, -1
	global_load_dwordx4 v[52:55], v5, s[24:25] offset:0
	global_load_dwordx4 v[56:59], v5, s[24:25] offset:16
	global_load_dwordx4 v[60:63], v5, s[24:25] offset:32
	global_load_dwordx4 v[64:67], v5, s[24:25] offset:48
	v_lshlrev_b32_e32 v88, 16, v68
	v_and_b32_e32 v89, 0xffff0000, v68
	v_lshlrev_b32_e32 v90, 16, v69
	v_and_b32_e32 v91, 0xffff0000, v69
	v_lshlrev_b32_e32 v92, 16, v70
	v_and_b32_e32 v93, 0xffff0000, v70
	v_lshlrev_b32_e32 v94, 16, v71
	v_and_b32_e32 v95, 0xffff0000, v71
	v_mov_b32_dpp v96, v68 quad_perm:[2,3,0,1] row_mask:0xf bank_mask:0xf
	v_mov_b32_dpp v97, v69 quad_perm:[2,3,0,1] row_mask:0xf bank_mask:0xf
	v_mov_b32_dpp v98, v70 quad_perm:[2,3,0,1] row_mask:0xf bank_mask:0xf
	v_mov_b32_dpp v99, v71 quad_perm:[2,3,0,1] row_mask:0xf bank_mask:0xf
	v_mul_f32_e32 v108, v88, v88
	v_fmac_f32_e32 v108, v89, v89
	v_fmac_f32_e32 v108, v90, v90
	v_fmac_f32_e32 v108, v91, v91
	v_fmac_f32_e32 v108, v92, v92
	v_fmac_f32_e32 v108, v93, v93
	v_fmac_f32_e32 v108, v94, v94
	v_fmac_f32_e32 v108, v95, v95
	s_nop 1
	v_add_f32_dpp v109, v108, v108 quad_perm:[1,0,3,2] row_mask:0xf bank_mask:0xf
	s_nop 1
	v_add_f32_dpp v108, v109, v109 quad_perm:[2,3,0,1] row_mask:0xf bank_mask:0xf
	s_nop 1
	v_add_f32_dpp v109, v108, v108 row_half_mirror row_mask:0xf bank_mask:0xf
	s_nop 1
	v_add_f32_dpp v108, v109, v109 row_mirror row_mask:0xf bank_mask:0xf
	v_lshlrev_b32_e32 v100, 16, v96
	v_and_b32_e32 v101, 0xffff0000, v96
	v_lshlrev_b32_e32 v102, 16, v97
	v_and_b32_e32 v103, 0xffff0000, v97
	v_lshlrev_b32_e32 v104, 16, v98
	v_and_b32_e32 v105, 0xffff0000, v98
	v_lshlrev_b32_e32 v106, 16, v99
	v_and_b32_e32 v107, 0xffff0000, v99
	v_fmamk_f32 v109, v108, 0x3c2aaaab, v14
	v_rsq_f32_e32 v110, v109
	s_nop 0
	v_mul_f32_e32 v111, v109, v110
	v_mul_f32_e32 v111, v111, v110
	v_fma_f32 v111, v111, -0.5, v15
	v_mul_f32_e32 v110, v110, v111
	v_mul_f32_e32 v112, v110, v32
	v_mul_f32_e32 v113, v110, v33
	v_mul_f32_e32 v114, v110, v34
	v_mul_f32_e32 v115, v110, v35
	v_mul_f32_e32 v116, v110, v36
	v_mul_f32_e32 v117, v110, v37
	v_mul_f32_e32 v118, v110, v38
	v_mul_f32_e32 v119, v110, v39
	v_mul_f32_e32 v88, v88, v112
	v_mul_f32_e32 v89, v89, v113
	v_mul_f32_e32 v90, v90, v114
	v_mul_f32_e32 v91, v91, v115
	v_mul_f32_e32 v92, v92, v116
	v_mul_f32_e32 v93, v93, v117
	v_mul_f32_e32 v94, v94, v118
	v_mul_f32_e32 v95, v95, v119
	v_mul_f32_e32 v100, v100, v110
	v_mul_f32_e32 v101, v101, v110
; #define UNPK8(v, f) do { f[0] = bflo(v.x); f[1] = bfhi(v.x); f[2] = bflo(v.y); f[3] = bfhi(v.y); f[4] = bflo(v.z); f[5] = bfhi(v.z); f[6] = bflo(v.w); f[7] = bfhi(v.w); } while (0)
; #define PACK8(v, f) do { v.x = pk2(f[0], f[1]); v.y = pk2(f[2], f[3]); v.z = pk2(f[4], f[5]); v.w = pk2(f[6], f[7]); } while (0)
; __global__ void __launch_bounds__(NTHREADS, 2) mega_fwd(Args args) {
;     ...
;         for (int it = gw; it < 2 * T * 2; it += NGW) {
;             const int which = it >= T * 2, j = which ? it - T * 2 : it, row = j >> 1, h = (j & 1) * 4 + (lane >> 4), sub = lane & 15;
;             const bool act = sub < 12;
;             const bf16* src = !which ? QF + (size_t)row * 768 + h * 96 + sub * 8 : (sub < 8 ? KV + (size_t)row * 1024 + h * 128 + sub * 8 : Z + (size_t)row * ZW + 1152 + (sub - 8) * 8);
;             const u32x4 zero4 = {0u, 0u, 0u, 0u};
;             const u32x4 v = act ? *(const u32x4*)src : zero4;
;             float ss = chunk_ss(v); ss += shfl_xor_l(ss, 1, lane); ss += shfl_xor_l(ss, 2, lane); ss += shfl_xor_l(ss, 4, lane); ss += shfl_xor_l(ss, 8, lane);
;             const float r = (1.0f / sqrtf(ss * (1.f / 96.f) + EPS)) * (which ? 1.0f : qsc);
;             const float* gain = which ? INP(13) : INP(12);
;             u32x4 pv;
;             pv.x = __builtin_amdgcn_ds_bpermute((lane ^ 2) << 2, v.x); pv.y = __builtin_amdgcn_ds_bpermute((lane ^ 2) << 2, v.y);
;             pv.z = __builtin_amdgcn_ds_bpermute((lane ^ 2) << 2, v.z); pv.w = __builtin_amdgcn_ds_bpermute((lane ^ 2) << 2, v.w);
;             if (act) {
;                 bf16* dst = (bf16*)(ws + (which ? A_KB : A_QB)) + (size_t)row * 768 + h * 96 + sub * 8;
;                 float f[8]; UNPK8(v, f);
;                 const float* g = gain + sub * 8;
; #pragma unroll
;                 for (int i = 0; i < 8; ++i) f[i] *= r * g[i];
;                 if (sub >= 8) {
;                     float pf_[8]; UNPK8(pv, pf_);
;                     const float* gp = gain + (sub ^ 2) * 8; const float2* cs = rope + (size_t)row * 16 + (sub & 1) * 8;
; #pragma unroll
;                     for (int i = 0; i < 8; ++i) { const float pn = pf_[i] * r * gp[i]; const float2 c = cs[i];
;                         f[i] = (sub < 10) ? (f[i] * c.x - pn * c.y) : (f[i] * c.x + pn * c.y); }
;                 }
;                 u32x4 o; PACK8(o, f); *(u32x4*)dst = o;
	v_mul_f32_e32 v102, v102, v110
	v_mul_f32_e32 v103, v103, v110
	v_mul_f32_e32 v104, v104, v110
	v_mul_f32_e32 v105, v105, v110
	v_mul_f32_e32 v106, v106, v110
	v_mul_f32_e32 v107, v107, v110
	v_mul_f32_e32 v100, v100, v40
	v_mul_f32_e32 v101, v101, v41
	v_mul_f32_e32 v102, v102, v42
	v_mul_f32_e32 v103, v103, v43
	v_mul_f32_e32 v104, v104, v44
	v_mul_f32_e32 v105, v105, v45
	v_mul_f32_e32 v106, v106, v46
	v_mul_f32_e32 v107, v107, v47
	v_mul_f32_e32 v112, v88, v72
	v_mul_f32_e32 v113, v89, v74
	v_mul_f32_e32 v114, v90, v76
	v_mul_f32_e32 v115, v91, v78
	v_mul_f32_e32 v116, v92, v80
	v_mul_f32_e32 v117, v93, v82
	v_mul_f32_e32 v118, v94, v84
	v_mul_f32_e32 v119, v95, v86
	v_fmac_f32_e32 v112, v100, v73
	v_fmac_f32_e32 v113, v101, v75
	v_fmac_f32_e32 v114, v102, v77
	v_fmac_f32_e32 v115, v103, v79
	v_fmac_f32_e32 v116, v104, v81
	v_fmac_f32_e32 v117, v105, v83
	v_fmac_f32_e32 v118, v106, v85
	v_fmac_f32_e32 v119, v107, v87
	v_cndmask_b32_e64 v88, v88, v112, s[6:7]
	v_cndmask_b32_e64 v89, v89, v113, s[6:7]
	v_cndmask_b32_e64 v90, v90, v114, s[6:7]
	v_cndmask_b32_e64 v91, v91, v115, s[6:7]
	v_cndmask_b32_e64 v92, v92, v116, s[6:7]
	v_cndmask_b32_e64 v93, v93, v117, s[6:7]
	v_cndmask_b32_e64 v94, v94, v118, s[6:7]
	v_cndmask_b32_e64 v95, v95, v119, s[6:7]
	v_cvt_pk_bf16_f32 v120, v88, v89
	v_cvt_pk_bf16_f32 v121, v90, v91
	v_cvt_pk_bf16_f32 v122, v92, v93
	v_cvt_pk_bf16_f32 v123, v94, v95
	s_mov_b64 exec, s[10:11]
	global_store_dwordx4 v3, v[120:123], s[30:31]
	s_mov_b64 exec, -1
	s_mov_b32 s3, s18
	s_waitcnt vmcnt(1)
	s_branch .Lp4_k_it0
.Lp4_k_last0:
	v_lshlrev_b32_e32 v88, 16, v48
	v_and_b32_e32 v89, 0xffff0000, v48
	v_lshlrev_b32_e32 v90, 16, v49
	v_and_b32_e32 v91, 0xffff0000, v49
	v_lshlrev_b32_e32 v92, 16, v50
	v_and_b32_e32 v93, 0xffff0000, v50
	v_lshlrev_b32_e32 v94, 16, v51
	v_and_b32_e32 v95, 0xffff0000, v51
	v_mov_b32_dpp v96, v48 quad_perm:[2,3,0,1] row_mask:0xf bank_mask:0xf
	v_mov_b32_dpp v97, v49 quad_perm:[2,3,0,1] row_mask:0xf bank_mask:0xf
	v_mov_b32_dpp v98, v50 quad_perm:[2,3,0,1] row_mask:0xf bank_mask:0xf
	v_mov_b32_dpp v99, v51 quad_perm:[2,3,0,1] row_mask:0xf bank_mask:0xf
	v_mul_f32_e32 v108, v88, v88
	v_fmac_f32_e32 v108, v89, v89
	v_fmac_f32_e32 v108, v90, v90
	v_fmac_f32_e32 v108, v91, v91
	v_fmac_f32_e32 v108, v92, v92
	v_fmac_f32_e32 v108, v93, v93
	v_fmac_f32_e32 v108, v94, v94
	v_fmac_f32_e32 v108, v95, v95
	s_nop 1
	v_add_f32_dpp v109, v108, v108 quad_perm:[1,0,3,2] row_mask:0xf bank_mask:0xf
	s_nop 1
	v_add_f32_dpp v108, v109, v109 quad_perm:[2,3,0,1] row_mask:0xf bank_mask:0xf
	s_nop 1
	v_add_f32_dpp v109, v108, v108 row_half_mirror row_mask:0xf bank_mask:0xf
	s_nop 1
	v_add_f32_dpp v108, v109, v109 row_mirror row_mask:0xf bank_mask:0xf
	v_lshlrev_b32_e32 v100, 16, v96
	v_and_b32_e32 v101, 0xffff0000, v96
	v_lshlrev_b32_e32 v102, 16, v97
	v_and_b32_e32 v103, 0xffff0000, v97
	v_lshlrev_b32_e32 v104, 16, v98
	v_and_b32_e32 v105, 0xffff0000, v98
	v_lshlrev_b32_e32 v106, 16, v99
	v_and_b32_e32 v107, 0xffff0000, v99
	v_fmamk_f32 v109, v108, 0x3c2aaaab, v14
	v_rsq_f32_e32 v110, v109
	s_nop 0
	v_mul_f32_e32 v111, v109, v110
	v_mul_f32_e32 v111, v111, v110
	v_fma_f32 v111, v111, -0.5, v15
	v_mul_f32_e32 v110, v110, v111
	v_mul_f32_e32 v112, v110, v32
	v_mul_f32_e32 v113, v110, v33
	v_mul_f32_e32 v114, v110, v34
	v_mul_f32_e32 v115, v110, v35
	v_mul_f32_e32 v116, v110, v36
	v_mul_f32_e32 v117, v110, v37
	v_mul_f32_e32 v118, v110, v38
	v_mul_f32_e32 v119, v110, v39
	v_mul_f32_e32 v88, v88, v112
	v_mul_f32_e32 v89, v89, v113
	v_mul_f32_e32 v90, v90, v114
	v_mul_f32_e32 v91, v91, v115
	v_mul_f32_e32 v92, v92, v116
	v_mul_f32_e32 v93, v93, v117
	v_mul_f32_e32 v94, v94, v118
	v_mul_f32_e32 v95, v95, v119
	v_mul_f32_e32 v100, v100, v110
	v_mul_f32_e32 v101, v101, v110
	v_mul_f32_e32 v102, v102, v110
	v_mul_f32_e32 v103, v103, v110
	v_mul_f32_e32 v104, v104, v110
	v_mul_f32_e32 v105, v105, v110
	v_mul_f32_e32 v106, v106, v110
	v_mul_f32_e32 v107, v107, v110
	v_mul_f32_e32 v100, v100, v40
	v_mul_f32_e32 v101, v101, v41
	v_mul_f32_e32 v102, v102, v42
	v_mul_f32_e32 v103, v103, v43
	v_mul_f32_e32 v104, v104, v44
	v_mul_f32_e32 v105, v105, v45
	v_mul_f32_e32 v106, v106, v46
	v_mul_f32_e32 v107, v107, v47
	v_mul_f32_e32 v112, v88, v52
	v_mul_f32_e32 v113, v89, v54
	v_mul_f32_e32 v114, v90, v56
	v_mul_f32_e32 v115, v91, v58
	v_mul_f32_e32 v116, v92, v60
	v_mul_f32_e32 v117, v93, v62
	v_mul_f32_e32 v118, v94, v64
	v_mul_f32_e32 v119, v95, v66
	v_fmac_f32_e32 v112, v100, v53
	v_fmac_f32_e32 v113, v101, v55
	v_fmac_f32_e32 v114, v102, v57
	v_fmac_f32_e32 v115, v103, v59
	v_fmac_f32_e32 v116, v104, v61
	v_fmac_f32_e32 v117, v105, v63
	v_fmac_f32_e32 v118, v106, v65
	v_fmac_f32_e32 v119, v107, v67
	v_cndmask_b32_e64 v88, v88, v112, s[6:7]
	v_cndmask_b32_e64 v89, v89, v113, s[6:7]
	v_cndmask_b32_e64 v90, v90, v114, s[6:7]
	v_cndmask_b32_e64 v91, v91, v115, s[6:7]
	v_cndmask_b32_e64 v92, v92, v116, s[6:7]
	v_cndmask_b32_e64 v93, v93, v117, s[6:7]
	v_cndmask_b32_e64 v94, v94, v118, s[6:7]
	v_cndmask_b32_e64 v95, v95, v119, s[6:7]
	v_cvt_pk_bf16_f32 v120, v88, v89
	v_cvt_pk_bf16_f32 v121, v90, v91
	v_cvt_pk_bf16_f32 v122, v92, v93
	v_cvt_pk_bf16_f32 v123, v94, v95
	s_mov_b64 exec, s[10:11]
	global_store_dwordx4 v3, v[120:123], s[26:27]
	s_mov_b64 exec, -1
	s_mov_b32 s3, s18
	s_branch .Lp4_k_done
; #define LAS __attribute__((address_space(3)))
; #define UNPK8(v, f) do { f[0] = bflo(v.x); f[1] = bfhi(v.x); f[2] = bflo(v.y); f[3] = bfhi(v.y); f[4] = bflo(v.z); f[5] = bfhi(v.z); f[6] = bflo(v.w); f[7] = bfhi(v.w); } while (0)
; #define PACK8(v, f) do { v.x = pk2(f[0], f[1]); v.y = pk2(f[2], f[3]); v.z = pk2(f[4], f[5]); v.w = pk2(f[6], f[7]); } while (0)
; template <int NC>
; __device__ __forceinline__ void transpose_tiles(LAS unsigned char* lds, const bf16* src, int pitch, int cbase, int cstride, int nct, bf16* dst, int W, int slen, int nrows, int bid_, int G_, int tid) {
;     constexpr int LS = NC * 64 + 8;
;     const int nsc = nct / NC, nst = (nrows / 64) * nsc;
;     LAS bf16* tl = (LAS bf16*)lds;
;     for (int st = bid_; st < nst; st += G_) {
;         const int rt = st / nsc, sc = st % nsc, r0 = rt * 64, b = r0 / slen, t0 = r0 % slen;
;         { const int tok = tid >> 3, ch = tid & 7; u32x4 v[NC];
; __global__ void __launch_bounds__(NTHREADS, 2) mega_fwd(Args args) {
;     ...
;             if (act) {
;                 bf16* dst = (bf16*)(ws + (which ? A_KB : A_QB)) + (size_t)row * 768 + h * 96 + sub * 8;
;                 float f[8]; UNPK8(v, f);
;                 const float* g = gain + sub * 8;
; #pragma unroll
;                 for (int i = 0; i < 8; ++i) f[i] *= r * g[i];
;                 if (sub >= 8) {
;                     float pf_[8]; UNPK8(pv, pf_);
;                     const float* gp = gain + (sub ^ 2) * 8; const float2* cs = rope + (size_t)row * 16 + (sub & 1) * 8;
; #pragma unroll
;                     for (int i = 0; i < 8; ++i) { const float pn = pf_[i] * r * gp[i]; const float2 c = cs[i];
;                         f[i] = (sub < 10) ? (f[i] * c.x - pn * c.y) : (f[i] * c.x + pn * c.y); }
;                 }
;                 u32x4 o; PACK8(o, f); *(u32x4*)dst = o;
;             }
;         }
;         transpose_tiles<4>(lds, KV, 1024, 64, 128, 8, (bf16*)(ws + A_VTB), 512, SEQ, T, bid, G, tid);
.Lp4_k_last1:
	v_lshlrev_b32_e32 v88, 16, v68
	v_and_b32_e32 v89, 0xffff0000, v68
	v_lshlrev_b32_e32 v90, 16, v69
	v_and_b32_e32 v91, 0xffff0000, v69
	v_lshlrev_b32_e32 v92, 16, v70
	v_and_b32_e32 v93, 0xffff0000, v70
	v_lshlrev_b32_e32 v94, 16, v71
	v_and_b32_e32 v95, 0xffff0000, v71
	v_mov_b32_dpp v96, v68 quad_perm:[2,3,0,1] row_mask:0xf bank_mask:0xf
	v_mov_b32_dpp v97, v69 quad_perm:[2,3,0,1] row_mask:0xf bank_mask:0xf
	v_mov_b32_dpp v98, v70 quad_perm:[2,3,0,1] row_mask:0xf bank_mask:0xf
	v_mov_b32_dpp v99, v71 quad_perm:[2,3,0,1] row_mask:0xf bank_mask:0xf
	v_mul_f32_e32 v108, v88, v88
	v_fmac_f32_e32 v108, v89, v89
	v_fmac_f32_e32 v108, v90, v90
	v_fmac_f32_e32 v108, v91, v91
	v_fmac_f32_e32 v108, v92, v92
	v_fmac_f32_e32 v108, v93, v93
	v_fmac_f32_e32 v108, v94, v94
	v_fmac_f32_e32 v108, v95, v95
	s_nop 1
	v_add_f32_dpp v109, v108, v108 quad_perm:[1,0,3,2] row_mask:0xf bank_mask:0xf
	s_nop 1
	v_add_f32_dpp v108, v109, v109 quad_perm:[2,3,0,1] row_mask:0xf bank_mask:0xf
	s_nop 1
	v_add_f32_dpp v109, v108, v108 row_half_mirror row_mask:0xf bank_mask:0xf
	s_nop 1
	v_add_f32_dpp v108, v109, v109 row_mirror row_mask:0xf bank_mask:0xf
	v_lshlrev_b32_e32 v100, 16, v96
	v_and_b32_e32 v101, 0xffff0000, v96
	v_lshlrev_b32_e32 v102, 16, v97
	v_and_b32_e32 v103, 0xffff0000, v97
	v_lshlrev_b32_e32 v104, 16, v98
	v_and_b32_e32 v105, 0xffff0000, v98
	v_lshlrev_b32_e32 v106, 16, v99
	v_and_b32_e32 v107, 0xffff0000, v99
	v_fmamk_f32 v109, v108, 0x3c2aaaab, v14
	v_rsq_f32_e32 v110, v109
	s_nop 0
	v_mul_f32_e32 v111, v109, v110
	v_mul_f32_e32 v111, v111, v110
	v_fma_f32 v111, v111, -0.5, v15
	v_mul_f32_e32 v110, v110, v111
	v_mul_f32_e32 v112, v110, v32
	v_mul_f32_e32 v113, v110, v33
	v_mul_f32_e32 v114, v110, v34
	v_mul_f32_e32 v115, v110, v35
	v_mul_f32_e32 v116, v110, v36
	v_mul_f32_e32 v117, v110, v37
	v_mul_f32_e32 v118, v110, v38
	v_mul_f32_e32 v119, v110, v39
	v_mul_f32_e32 v88, v88, v112
	v_mul_f32_e32 v89, v89, v113
	v_mul_f32_e32 v90, v90, v114
	v_mul_f32_e32 v91, v91, v115
	v_mul_f32_e32 v92, v92, v116
	v_mul_f32_e32 v93, v93, v117
	v_mul_f32_e32 v94, v94, v118
	v_mul_f32_e32 v95, v95, v119
	v_mul_f32_e32 v100, v100, v110
	v_mul_f32_e32 v101, v101, v110
	v_mul_f32_e32 v102, v102, v110
	v_mul_f32_e32 v103, v103, v110
	v_mul_f32_e32 v104, v104, v110
	v_mul_f32_e32 v105, v105, v110
	v_mul_f32_e32 v106, v106, v110
	v_mul_f32_e32 v107, v107, v110
	v_mul_f32_e32 v100, v100, v40
	v_mul_f32_e32 v101, v101, v41
	v_mul_f32_e32 v102, v102, v42
	v_mul_f32_e32 v103, v103, v43
	v_mul_f32_e32 v104, v104, v44
	v_mul_f32_e32 v105, v105, v45
	v_mul_f32_e32 v106, v106, v46
	v_mul_f32_e32 v107, v107, v47
	v_mul_f32_e32 v112, v88, v72
	v_mul_f32_e32 v113, v89, v74
	v_mul_f32_e32 v114, v90, v76
	v_mul_f32_e32 v115, v91, v78
	v_mul_f32_e32 v116, v92, v80
	v_mul_f32_e32 v117, v93, v82
	v_mul_f32_e32 v118, v94, v84
	v_mul_f32_e32 v119, v95, v86
	v_fmac_f32_e32 v112, v100, v73
	v_fmac_f32_e32 v113, v101, v75
	v_fmac_f32_e32 v114, v102, v77
	v_fmac_f32_e32 v115, v103, v79
	v_fmac_f32_e32 v116, v104, v81
	v_fmac_f32_e32 v117, v105, v83
	v_fmac_f32_e32 v118, v106, v85
	v_fmac_f32_e32 v119, v107, v87
	v_cndmask_b32_e64 v88, v88, v112, s[6:7]
	v_cndmask_b32_e64 v89, v89, v113, s[6:7]
	v_cndmask_b32_e64 v90, v90, v114, s[6:7]
	v_cndmask_b32_e64 v91, v91, v115, s[6:7]
	v_cndmask_b32_e64 v92, v92, v116, s[6:7]
	v_cndmask_b32_e64 v93, v93, v117, s[6:7]
	v_cndmask_b32_e64 v94, v94, v118, s[6:7]
	v_cndmask_b32_e64 v95, v95, v119, s[6:7]
	v_cvt_pk_bf16_f32 v120, v88, v89
	v_cvt_pk_bf16_f32 v121, v90, v91
	v_cvt_pk_bf16_f32 v122, v92, v93
	v_cvt_pk_bf16_f32 v123, v94, v95
	s_mov_b64 exec, s[10:11]
	global_store_dwordx4 v3, v[120:123], s[30:31]
	s_mov_b64 exec, -1
	s_mov_b32 s3, s18
	s_branch .Lp4_k_done
.Lp4_k_done:
	s_branch .LBB0_462
.LBB0_462:
	s_andn2_b64 vcc, exec, s[14:15]
	s_cbranch_vccnz .LBB0_465
	s_load_dwordx4 s[4:7], s[82:83], 0x100
	v_and_b32_e32 v6, 7, v9
	v_ashrrev_i32_e32 v0, 3, v9
	v_lshlrev_b32_e32 v8, 4, v6
	v_mov_b32_e32 v9, 0
	s_waitcnt lgkmcnt(0)
	v_lshl_add_u64 v[2:3], s[6:7], 0, v[8:9]
	s_mov_b64 s[4:5], 0x4200080
	v_lshl_add_u64 v[2:3], v[2:3], 0, s[4:5]
	s_movk_i32 s3, 0x210
	v_readlane_b32 s4, v252, 39
	v_mul_lo_u32 v1, v0, s3
	v_readlane_b32 s5, v252, 40
	v_add_u32_e32 v7, 0, v1
	v_mul_u32_u24_e32 v6, 0x1080, v6
	v_lshl_add_u64 v[4:5], s[4:5], 0, v[8:9]
	v_lshlrev_b32_e32 v9, 1, v0
	v_ashrrev_i32_e32 v1, 31, v0
	v_add3_u32 v6, 0, v6, v9
	s_lshl_b32 s3, s84, 9
	s_lshl_b32 s4, s2, 9
	s_lshl_b32 s5, s84, 8
	s_lshl_b32 s6, s2, 8
	v_add_u32_e32 v7, v7, v8
	s_mov_b32 s7, s84

; #define LAS __attribute__((address_space(3)))
; template <int DQK, int DV, int FLAGS, int qp, int kp, int vts, int op> ...
;     ...
;             f32x2 rs2 = {0.f, 0.f};
; #pragma unroll
;             for (int r = 0; r < 16; ++r) { p0[r] = __builtin_amdgcn_exp2f(p0[r]); p1[r] = __builtin_amdgcn_exp2f(p1[r]); }
; #pragma unroll
;             for (int r = 0; r < 16; r += 2) { rs2 += (f32x2){p0[r], p0[r + 1]}; rs2 += (f32x2){p1[r], p1[r + 1]}; }
;             l += rs2.x + rs2.y;
;             bf16x8 pf[4];
;             pf[0] = pack_bf16x8(p0, 0); pf[1] = pack_bf16x8(p0, 8); pf[2] = pack_bf16x8(p1, 0); pf[3] = pack_bf16x8(p1, 8);
;             __builtin_amdgcn_sched_barrier(0);
; #pragma unroll
;             for (int d = 0; d < NDB; ++d) {
;                 if (d + 1 < NDB) {
; #pragma unroll
;                     for (int ks = 0; ks < 4; ++ks) vf[(d + 1) & 1][ks] = *(const LAS bf16x8*)(vb + (d + 1) * 32 * VROW + ks * 32);
;                 }
; #pragma unroll
;                 for (int ks = 0; ks < 4; ++ks) o[d] = __builtin_amdgcn_mfma_f32_32x32x16_bf16(vf[d & 1][ks], pf[ks], o[d], 0, 0, 0);
;                 __builtin_amdgcn_sched_barrier(0);
;             }
.Ld_noqk0:
.Ld_top0:
	s_cmp_le_i32 s23, s24
	s_cbranch_scc1 .Ld_gen0
	s_add_i32 s13, s23, 1
	s_cmp_ge_i32 s13, s3
	s_cbranch_scc1 .Ld_gen0
	s_add_i32 s12, s23, -1
	s_and_b32 s12, s12, 3
	s_mulk_i32 s12, 0x6c00
	v_add3_u32 v245, s12, v203, v194
	ds_read_b128 v[224:227], v245 offset:13824
	ds_read_b128 v[228:231], v245 offset:13856
	ds_read_b128 v[232:235], v245 offset:13888
	ds_read_b128 v[236:239], v245 offset:13920
	s_add_i32 s12, s23, 1
	s_and_b32 s12, s12, 3
	s_mulk_i32 s12, 0x6c00
	v_add3_u32 v244, s12, v201, v194
	s_and_b32 s12, s23, 3
	s_mulk_i32 s12, 0x6c00
	v_add3_u32 v251, s12, v203, v194
	v_mfma_f32_32x32x16_bf16 v[64:79], v[160:163], v[112:115], v[64:79]
	v_exp_f32_e32 v80, v80
	v_exp_f32_e32 v81, v81
	v_exp_f32_e32 v96, v96
	v_exp_f32_e32 v97, v97
	v_add_u32_e32 v246, 64, v205
	v_mov_b32_e32 v240, v80
	v_mfma_f32_32x32x16_bf16 v[64:79], v[164:167], v[116:119], v[64:79]
	v_mov_b32_e32 v241, v81
	v_exp_f32_e32 v82, v82
	v_exp_f32_e32 v83, v83
	v_cvt_f32_i32_e32 v246, v246
	v_add_f32_e32 v240, v96, v240
	v_add_f32_e32 v241, v97, v241
	v_mfma_f32_32x32x16_bf16 v[64:79], v[168:171], v[120:123], v[64:79]
	v_exp_f32_e32 v98, v98
	v_exp_f32_e32 v99, v99
	v_fma_f32 v242, -v14, v246, -v222
	v_add_f32_e32 v240, v82, v240
	v_add_f32_e32 v241, v83, v241
	v_exp_f32_e32 v84, v84
	v_mfma_f32_32x32x16_bf16 v[64:79], v[172:175], v[124:127], v[64:79]
	v_exp_f32_e32 v85, v85
	v_fma_f32 v128, v14, s8, v242
	v_add_f32_e32 v240, v98, v240
	v_add_f32_e32 v241, v99, v241
	v_exp_f32_e32 v100, v100
	v_exp_f32_e32 v101, v101
	ds_read_b128 v[160:163], v245 offset:18432
	ds_read_b128 v[164:167], v245 offset:18464
	ds_read_b128 v[168:171], v245 offset:18496
	ds_read_b128 v[172:175], v245 offset:18528
	s_waitcnt lgkmcnt(4)
	v_mfma_f32_32x32x16_bf16 v[48:63], v[224:227], v[112:115], v[48:63]
	v_fma_f32 v129, v14, s9, v242
	v_add_f32_e32 v240, v84, v240
	v_add_f32_e32 v241, v85, v241
	v_exp_f32_e32 v86, v86
	v_exp_f32_e32 v87, v87
	v_fma_f32 v130, v14, s96, v242
	v_mfma_f32_32x32x16_bf16 v[48:63], v[228:231], v[116:119], v[48:63]
	v_add_f32_e32 v240, v100, v240
	v_add_f32_e32 v241, v101, v241
	v_exp_f32_e32 v102, v102
	v_exp_f32_e32 v103, v103
	v_fma_f32 v131, v14, s97, v242
	v_add_f32_e32 v240, v86, v240
	v_mfma_f32_32x32x16_bf16 v[48:63], v[232:235], v[120:123], v[48:63]
	v_add_f32_e32 v241, v87, v241
	v_exp_f32_e32 v88, v88
	v_exp_f32_e32 v89, v89
	v_fma_f32 v132, v14, s94, v242
	v_add_f32_e32 v240, v102, v240
	v_add_f32_e32 v241, v103, v241
	v_mfma_f32_32x32x16_bf16 v[48:63], v[236:239], v[124:127], v[48:63]
	v_exp_f32_e32 v104, v104
	v_exp_f32_e32 v105, v105
	v_fma_f32 v133, v14, s95, v242
	v_add_f32_e32 v240, v88, v240
	v_add_f32_e32 v241, v89, v241
	v_exp_f32_e32 v90, v90
	ds_read_b128 v[224:227], v245 offset:23040
	ds_read_b128 v[228:231], v245 offset:23072
	ds_read_b128 v[232:235], v245 offset:23104
	ds_read_b128 v[236:239], v245 offset:23136
	s_waitcnt lgkmcnt(4)
	s_add_i32 s12, s23, 2
	s_cmp_ge_i32 s12, s3
	s_cbranch_scc1 .Ld_nols_s0
	s_and_b32 s13, s12, 3
	s_mulk_i32 s13, 0x6c00
	s_waitcnt vmcnt(0)
	v_add_u32_e32 v248, s13, v204
	v_add_u32_e32 v249, s13, v200
	v_add_u32_e32 v250, s13, v202
	ds_write_b128 v248, v[148:151]
	ds_write_b128 v249, v[152:155] offset:9216
	ds_write_b128 v250, v[156:159] offset:9216
	s_add_i32 s12, s23, 3
	s_cmp_ge_i32 s12, s3
	s_cbranch_scc1 .Ld_nols_s0
	s_ashr_i32 s35, s34, 31
	s_lshl_b64 s[6:7], s[34:35], 17
	s_lshl_b64 s[10:11], s[34:35], 7
	s_add_u32 s10, s18, s10
	s_addc_u32 s11, s19, s11
	v_lshl_add_u64 v[246:247], v[206:207], 0, s[6:7]
	global_load_dwordx4 v[148:151], v[246:247], off
	v_lshl_add_u64 v[246:247], s[10:11], 0, v[0:1]
	global_load_dwordx4 v[152:155], v[246:247], off
	v_lshl_add_u64 v[246:247], s[10:11], 0, v[196:197]
	global_load_dwordx4 v[156:159], v[246:247], off
	s_add_i32 s34, s34, -1
; #define LAS __attribute__((address_space(3)))
; template <int DQK, int DV, int FLAGS, int qp, int kp, int vts, int op> ...
;     ...
;             f32x2 rs2 = {0.f, 0.f};
; #pragma unroll
;             for (int r = 0; r < 16; ++r) { p0[r] = __builtin_amdgcn_exp2f(p0[r]); p1[r] = __builtin_amdgcn_exp2f(p1[r]); }
; #pragma unroll
;             for (int r = 0; r < 16; r += 2) { rs2 += (f32x2){p0[r], p0[r + 1]}; rs2 += (f32x2){p1[r], p1[r + 1]}; }
;             l += rs2.x + rs2.y;
;             bf16x8 pf[4];
;             pf[0] = pack_bf16x8(p0, 0); pf[1] = pack_bf16x8(p0, 8); pf[2] = pack_bf16x8(p1, 0); pf[3] = pack_bf16x8(p1, 8);
;             __builtin_amdgcn_sched_barrier(0);
; #pragma unroll
;             for (int d = 0; d < NDB; ++d) {
;                 if (d + 1 < NDB) {
; #pragma unroll
;                     for (int ks = 0; ks < 4; ++ks) vf[(d + 1) & 1][ks] = *(const LAS bf16x8*)(vb + (d + 1) * 32 * VROW + ks * 32);
;                 }
; #pragma unroll
;                 for (int ks = 0; ks < 4; ++ks) o[d] = __builtin_amdgcn_mfma_f32_32x32x16_bf16(vf[d & 1][ks], pf[ks], o[d], 0, 0, 0);
;                 __builtin_amdgcn_sched_barrier(0);
;             }
.Ld_nols_s0:
	v_mfma_f32_32x32x16_bf16 v[32:47], v[160:163], v[112:115], v[32:47]
	v_exp_f32_e32 v91, v91
	v_fma_f32 v134, v14, s92, v242
	v_add_f32_e32 v240, v104, v240
	v_add_f32_e32 v241, v105, v241
	v_exp_f32_e32 v106, v106
	v_exp_f32_e32 v107, v107
	v_mfma_f32_32x32x16_bf16 v[32:47], v[164:167], v[116:119], v[32:47]
	v_fma_f32 v135, v14, s93, v242
	v_add_f32_e32 v240, v90, v240
	v_add_f32_e32 v241, v91, v241
	v_exp_f32_e32 v92, v92
	v_exp_f32_e32 v93, v93
	v_fma_f32 v136, v14, s90, v242
	v_mfma_f32_32x32x16_bf16 v[32:47], v[168:171], v[120:123], v[32:47]
	v_add_f32_e32 v240, v106, v240
	v_add_f32_e32 v241, v107, v241
	v_exp_f32_e32 v108, v108
	v_exp_f32_e32 v109, v109
	v_fma_f32 v137, v14, s91, v242
	v_add_f32_e32 v240, v92, v240
	v_mfma_f32_32x32x16_bf16 v[32:47], v[172:175], v[124:127], v[32:47]
	v_add_f32_e32 v241, v93, v241
	v_exp_f32_e32 v94, v94
	v_exp_f32_e32 v95, v95
	v_fma_f32 v138, v14, s88, v242
	v_add_f32_e32 v240, v108, v240
	v_add_f32_e32 v241, v109, v241
	ds_read_b128 v[160:163], v244 offset:4608
	ds_read_b128 v[164:167], v244 offset:4640
	ds_read_b128 v[168:171], v244 offset:4672
	ds_read_b128 v[172:175], v244 offset:4704
	s_waitcnt lgkmcnt(4)
	v_mfma_f32_32x32x16_bf16 v[16:31], v[224:227], v[112:115], v[16:31]
	v_exp_f32_e32 v110, v110
	v_exp_f32_e32 v111, v111
	v_fma_f32 v139, v14, s89, v242
	v_add_f32_e32 v240, v94, v240
	v_add_f32_e32 v241, v95, v241
	v_fma_f32 v140, v14, s86, v242
	v_mfma_f32_32x32x16_bf16 v[16:31], v[228:231], v[116:119], v[16:31]
	v_fma_f32 v141, v14, s87, v242
	v_fma_f32 v142, v14, s78, v242
	v_fma_f32 v143, v14, s79, v242
	v_mfma_f32_32x32x16_bf16 v[16:31], v[232:235], v[120:123], v[16:31]
	v_mfma_f32_32x32x16_bf16 v[16:31], v[236:239], v[124:127], v[16:31]
	ds_read_b128 v[224:227], v244 offset:0
	ds_read_b128 v[228:231], v244 offset:32
	ds_read_b128 v[232:235], v244 offset:64
	ds_read_b128 v[236:239], v244 offset:96
	s_waitcnt lgkmcnt(4)
	v_mfma_f32_32x32x16_bf16 v[128:143], v[160:163], v[2:5], v[128:143]
	v_mov_b32_e32 v112, v242
	v_add_f32_e32 v113, v14, v242
	v_fma_f32 v114, v14, s62, v242
	v_fma_f32 v115, v14, s63, v242
	v_mfma_f32_32x32x16_bf16 v[128:143], v[164:167], v[6:9], v[128:143]
	v_fma_f32 v116, v14, s64, v242
	v_fma_f32 v117, v14, s65, v242
	v_fma_f32 v118, v14, s66, v242
	v_fma_f32 v119, v14, s67, v242
	v_mfma_f32_32x32x16_bf16 v[128:143], v[168:171], v[10:13], v[128:143]
	v_fma_f32 v120, v14, s68, v242
	v_fma_f32 v121, v14, s69, v242
	v_fma_f32 v122, v14, s70, v242
	v_fma_f32 v123, v14, s71, v242
	v_mfma_f32_32x32x16_bf16 v[128:143], v[172:175], v[144:147], v[128:143]
	v_fma_f32 v124, v14, s72, v242
	v_fma_f32 v125, v14, s73, v242
	v_fma_f32 v126, v14, s76, v242
	v_fma_f32 v127, v14, s77, v242
	ds_read_b128 v[160:163], v251 offset:9216
	ds_read_b128 v[164:167], v251 offset:9248
	ds_read_b128 v[168:171], v251 offset:9280
	ds_read_b128 v[172:175], v251 offset:9312
	s_waitcnt lgkmcnt(4)
	v_mfma_f32_32x32x16_bf16 v[112:127], v[224:227], v[2:5], v[112:127]
	s_nop 0
	v_add_f32_e32 v240, v110, v240
	v_add_f32_e32 v241, v111, v241
	v_cvt_pk_bf16_f32 v80, v80, v81
	v_cvt_pk_bf16_f32 v81, v82, v83
	v_cvt_pk_bf16_f32 v82, v84, v85
	v_mfma_f32_32x32x16_bf16 v[112:127], v[228:231], v[6:9], v[112:127]
	v_cvt_pk_bf16_f32 v83, v86, v87
	v_cvt_pk_bf16_f32 v84, v88, v89
	v_cvt_pk_bf16_f32 v85, v90, v91
	v_cvt_pk_bf16_f32 v86, v92, v93
	v_cvt_pk_bf16_f32 v87, v94, v95
	v_cvt_pk_bf16_f32 v88, v96, v97
	v_mfma_f32_32x32x16_bf16 v[112:127], v[232:235], v[10:13], v[112:127]
	v_cvt_pk_bf16_f32 v89, v98, v99
	v_cvt_pk_bf16_f32 v90, v100, v101
	v_cvt_pk_bf16_f32 v91, v102, v103
	v_cvt_pk_bf16_f32 v92, v104, v105
	v_cvt_pk_bf16_f32 v93, v106, v107
	v_cvt_pk_bf16_f32 v94, v108, v109
	v_mfma_f32_32x32x16_bf16 v[112:127], v[236:239], v[144:147], v[112:127]
	v_cvt_pk_bf16_f32 v95, v110, v111
	v_add_f32_e32 v247, v240, v241
	v_add_f32_e32 v199, v199, v247
	s_branch .Ld_tail0
.Ld_gen0:
	s_add_i32 s12, s23, 2
	s_cmp_ge_i32 s12, s3
	s_cbranch_scc1 .Ld_nols_p0
	s_and_b32 s13, s12, 3
	s_mulk_i32 s13, 0x6c00
	s_waitcnt vmcnt(0)
	v_add_u32_e32 v248, s13, v204
	v_add_u32_e32 v249, s13, v200
	v_add_u32_e32 v250, s13, v202
	ds_write_b128 v248, v[148:151]
	ds_write_b128 v249, v[152:155] offset:9216
	ds_write_b128 v250, v[156:159] offset:9216
	s_add_i32 s12, s23, 3
	s_cmp_ge_i32 s12, s3
	s_cbranch_scc1 .Ld_nols_p0
	s_ashr_i32 s35, s34, 31
	s_lshl_b64 s[6:7], s[34:35], 17
	s_lshl_b64 s[10:11], s[34:35], 7
	s_add_u32 s10, s18, s10
	s_addc_u32 s11, s19, s11
	v_lshl_add_u64 v[246:247], v[206:207], 0, s[6:7]
	global_load_dwordx4 v[148:151], v[246:247], off
	v_lshl_add_u64 v[246:247], s[10:11], 0, v[0:1]
	global_load_dwordx4 v[152:155], v[246:247], off
	v_lshl_add_u64 v[246:247], s[10:11], 0, v[196:197]
	global_load_dwordx4 v[156:159], v[246:247], off
	s_add_i32 s34, s34, -1
.Ld_nols_p0:
	s_cmp_le_i32 s23, s24
	s_cbranch_scc1 .Ld_nopv_p0
	s_waitcnt lgkmcnt(0)
	s_add_i32 s12, s23, -1
	s_and_b32 s12, s12, 3
	s_mulk_i32 s12, 0x6c00
	v_add3_u32 v245, s12, v203, v194
	ds_read_b128 v[224:227], v245 offset:13824
	ds_read_b128 v[228:231], v245 offset:13856
	ds_read_b128 v[232:235], v245 offset:13888
	ds_read_b128 v[236:239], v245 offset:13920
	v_mfma_f32_32x32x16_bf16 v[64:79], v[160:163], v[112:115], v[64:79]
	v_mfma_f32_32x32x16_bf16 v[64:79], v[164:167], v[116:119], v[64:79]
	v_mfma_f32_32x32x16_bf16 v[64:79], v[168:171], v[120:123], v[64:79]
	v_mfma_f32_32x32x16_bf16 v[64:79], v[172:175], v[124:127], v[64:79]
	ds_read_b128 v[160:163], v245 offset:18432
	ds_read_b128 v[164:167], v245 offset:18464
	ds_read_b128 v[168:171], v245 offset:18496
	ds_read_b128 v[172:175], v245 offset:18528
	s_waitcnt lgkmcnt(4)
	v_mfma_f32_32x32x16_bf16 v[48:63], v[224:227], v[112:115], v[48:63]
	v_mfma_f32_32x32x16_bf16 v[48:63], v[228:231], v[116:119], v[48:63]
	v_mfma_f32_32x32x16_bf16 v[48:63], v[232:235], v[120:123], v[48:63]
	v_mfma_f32_32x32x16_bf16 v[48:63], v[236:239], v[124:127], v[48:63]
	ds_read_b128 v[224:227], v245 offset:23040
	ds_read_b128 v[228:231], v245 offset:23072
	ds_read_b128 v[232:235], v245 offset:23104
	ds_read_b128 v[236:239], v245 offset:23136
	s_waitcnt lgkmcnt(4)
	v_mfma_f32_32x32x16_bf16 v[32:47], v[160:163], v[112:115], v[32:47]
	v_mfma_f32_32x32x16_bf16 v[32:47], v[164:167], v[116:119], v[32:47]
	v_mfma_f32_32x32x16_bf16 v[32:47], v[168:171], v[120:123], v[32:47]
	v_mfma_f32_32x32x16_bf16 v[32:47], v[172:175], v[124:127], v[32:47]
	s_waitcnt lgkmcnt(0)
	v_mfma_f32_32x32x16_bf16 v[16:31], v[224:227], v[112:115], v[16:31]
	v_mfma_f32_32x32x16_bf16 v[16:31], v[228:231], v[116:119], v[16:31]
	v_mfma_f32_32x32x16_bf16 v[16:31], v[232:235], v[120:123], v[16:31]
	v_mfma_f32_32x32x16_bf16 v[16:31], v[236:239], v[124:127], v[16:31]

; #define LAS __attribute__((address_space(3)))
; template <int DQK, int DV, int FLAGS, int qp, int kp, int vts, int op> ...
;     ...
;             f32x2 rs2 = {0.f, 0.f};
; #pragma unroll
;             for (int r = 0; r < 16; ++r) { p0[r] = __builtin_amdgcn_exp2f(p0[r]); p1[r] = __builtin_amdgcn_exp2f(p1[r]); }
; #pragma unroll
;             for (int r = 0; r < 16; r += 2) { rs2 += (f32x2){p0[r], p0[r + 1]}; rs2 += (f32x2){p1[r], p1[r + 1]}; }
;             l += rs2.x + rs2.y;
;             bf16x8 pf[4];
;             pf[0] = pack_bf16x8(p0, 0); pf[1] = pack_bf16x8(p0, 8); pf[2] = pack_bf16x8(p1, 0); pf[3] = pack_bf16x8(p1, 8);
;             __builtin_amdgcn_sched_barrier(0);
; #pragma unroll
;             for (int d = 0; d < NDB; ++d) {
;                 if (d + 1 < NDB) {
; #pragma unroll
;                     for (int ks = 0; ks < 4; ++ks) vf[(d + 1) & 1][ks] = *(const LAS bf16x8*)(vb + (d + 1) * 32 * VROW + ks * 32);
;                 }
; #pragma unroll
;                 for (int ks = 0; ks < 4; ++ks) o[d] = __builtin_amdgcn_mfma_f32_32x32x16_bf16(vf[d & 1][ks], pf[ks], o[d], 0, 0, 0);
;                 __builtin_amdgcn_sched_barrier(0);
;             }
.Ld_top1:
	s_cmp_le_i32 s23, s24
	s_cbranch_scc1 .Ld_gen1
	s_add_i32 s13, s23, 1
	s_cmp_ge_i32 s13, s3
	s_cbranch_scc1 .Ld_gen1
	s_add_i32 s12, s23, -1
	s_and_b32 s12, s12, 3
	s_mulk_i32 s12, 0x6c00
	v_add3_u32 v245, s12, v203, v194
	ds_read_b128 v[224:227], v245 offset:13824
	ds_read_b128 v[228:231], v245 offset:13856
	ds_read_b128 v[232:235], v245 offset:13888
	ds_read_b128 v[236:239], v245 offset:13920
	s_add_i32 s12, s23, 1
	s_and_b32 s12, s12, 3
	s_mulk_i32 s12, 0x6c00
	v_add3_u32 v244, s12, v201, v194
	s_and_b32 s12, s23, 3
	s_mulk_i32 s12, 0x6c00
	v_add3_u32 v251, s12, v203, v194
	v_mfma_f32_32x32x16_bf16 v[64:79], v[160:163], v[80:83], v[64:79]
	v_exp_f32_e32 v112, v112
	v_exp_f32_e32 v113, v113
	v_exp_f32_e32 v128, v128
	v_exp_f32_e32 v129, v129
	v_add_u32_e32 v246, 64, v205
	v_mov_b32_e32 v240, v112
	v_mfma_f32_32x32x16_bf16 v[64:79], v[164:167], v[84:87], v[64:79]
	v_mov_b32_e32 v241, v113
	v_exp_f32_e32 v114, v114
	v_exp_f32_e32 v115, v115
	v_cvt_f32_i32_e32 v246, v246
	v_add_f32_e32 v240, v128, v240
	v_add_f32_e32 v241, v129, v241
	v_mfma_f32_32x32x16_bf16 v[64:79], v[168:171], v[88:91], v[64:79]
	v_exp_f32_e32 v130, v130
	v_exp_f32_e32 v131, v131
	v_fma_f32 v242, -v14, v246, -v222
	v_add_f32_e32 v240, v114, v240
	v_add_f32_e32 v241, v115, v241
	v_exp_f32_e32 v116, v116
	v_mfma_f32_32x32x16_bf16 v[64:79], v[172:175], v[92:95], v[64:79]
	v_exp_f32_e32 v117, v117
	v_fma_f32 v96, v14, s8, v242
	v_add_f32_e32 v240, v130, v240
	v_add_f32_e32 v241, v131, v241
	v_exp_f32_e32 v132, v132
	v_exp_f32_e32 v133, v133
	ds_read_b128 v[160:163], v245 offset:18432
	ds_read_b128 v[164:167], v245 offset:18464
	ds_read_b128 v[168:171], v245 offset:18496
	ds_read_b128 v[172:175], v245 offset:18528
	s_waitcnt lgkmcnt(4)
	v_mfma_f32_32x32x16_bf16 v[48:63], v[224:227], v[80:83], v[48:63]
	v_fma_f32 v97, v14, s9, v242
	v_add_f32_e32 v240, v116, v240
	v_add_f32_e32 v241, v117, v241
	v_exp_f32_e32 v118, v118
	v_exp_f32_e32 v119, v119
	v_fma_f32 v98, v14, s96, v242
	v_mfma_f32_32x32x16_bf16 v[48:63], v[228:231], v[84:87], v[48:63]
	v_add_f32_e32 v240, v132, v240
	v_add_f32_e32 v241, v133, v241
	v_exp_f32_e32 v134, v134
	v_exp_f32_e32 v135, v135
	v_fma_f32 v99, v14, s97, v242
	v_add_f32_e32 v240, v118, v240
	v_mfma_f32_32x32x16_bf16 v[48:63], v[232:235], v[88:91], v[48:63]
	v_add_f32_e32 v241, v119, v241
	v_exp_f32_e32 v120, v120
	v_exp_f32_e32 v121, v121
	v_fma_f32 v100, v14, s94, v242
	v_add_f32_e32 v240, v134, v240
	v_add_f32_e32 v241, v135, v241
	v_mfma_f32_32x32x16_bf16 v[48:63], v[236:239], v[92:95], v[48:63]
	v_exp_f32_e32 v136, v136
	v_exp_f32_e32 v137, v137
	v_fma_f32 v101, v14, s95, v242
	v_add_f32_e32 v240, v120, v240
	v_add_f32_e32 v241, v121, v241
	v_exp_f32_e32 v122, v122
	ds_read_b128 v[224:227], v245 offset:23040
	ds_read_b128 v[228:231], v245 offset:23072
	ds_read_b128 v[232:235], v245 offset:23104
	ds_read_b128 v[236:239], v245 offset:23136
	s_waitcnt lgkmcnt(4)
	s_add_i32 s12, s23, 2
	s_cmp_ge_i32 s12, s3
	s_cbranch_scc1 .Ld_nols_s1
	s_and_b32 s13, s12, 3
	s_mulk_i32 s13, 0x6c00
	s_waitcnt vmcnt(0)
	v_add_u32_e32 v248, s13, v204
	v_add_u32_e32 v249, s13, v200
	v_add_u32_e32 v250, s13, v202
	ds_write_b128 v248, v[148:151]
	ds_write_b128 v249, v[152:155] offset:9216
	ds_write_b128 v250, v[156:159] offset:9216
	s_add_i32 s12, s23, 3
	s_cmp_ge_i32 s12, s3
	s_cbranch_scc1 .Ld_nols_s1
	s_ashr_i32 s35, s34, 31
	s_lshl_b64 s[6:7], s[34:35], 17
	s_lshl_b64 s[10:11], s[34:35], 7
	s_add_u32 s10, s18, s10
	s_addc_u32 s11, s19, s11
	v_lshl_add_u64 v[246:247], v[206:207], 0, s[6:7]
	global_load_dwordx4 v[148:151], v[246:247], off
	v_lshl_add_u64 v[246:247], s[10:11], 0, v[0:1]
	global_load_dwordx4 v[152:155], v[246:247], off
	v_lshl_add_u64 v[246:247], s[10:11], 0, v[196:197]
	global_load_dwordx4 v[156:159], v[246:247], off
	s_add_i32 s34, s34, -1
; #define LAS __attribute__((address_space(3)))
; template <int DQK, int DV, int FLAGS, int qp, int kp, int vts, int op> ...
;     ...
;             f32x2 rs2 = {0.f, 0.f};
; #pragma unroll
;             for (int r = 0; r < 16; ++r) { p0[r] = __builtin_amdgcn_exp2f(p0[r]); p1[r] = __builtin_amdgcn_exp2f(p1[r]); }
; #pragma unroll
;             for (int r = 0; r < 16; r += 2) { rs2 += (f32x2){p0[r], p0[r + 1]}; rs2 += (f32x2){p1[r], p1[r + 1]}; }
;             l += rs2.x + rs2.y;
;             bf16x8 pf[4];
;             pf[0] = pack_bf16x8(p0, 0); pf[1] = pack_bf16x8(p0, 8); pf[2] = pack_bf16x8(p1, 0); pf[3] = pack_bf16x8(p1, 8);
;             __builtin_amdgcn_sched_barrier(0);
; #pragma unroll
;             for (int d = 0; d < NDB; ++d) {
;                 if (d + 1 < NDB) {
; #pragma unroll
;                     for (int ks = 0; ks < 4; ++ks) vf[(d + 1) & 1][ks] = *(const LAS bf16x8*)(vb + (d + 1) * 32 * VROW + ks * 32);
;                 }
; #pragma unroll
;                 for (int ks = 0; ks < 4; ++ks) o[d] = __builtin_amdgcn_mfma_f32_32x32x16_bf16(vf[d & 1][ks], pf[ks], o[d], 0, 0, 0);
;                 __builtin_amdgcn_sched_barrier(0);
;             }
.Ld_nols_s1:
	v_mfma_f32_32x32x16_bf16 v[32:47], v[160:163], v[80:83], v[32:47]
	v_exp_f32_e32 v123, v123
	v_fma_f32 v102, v14, s92, v242
	v_add_f32_e32 v240, v136, v240
	v_add_f32_e32 v241, v137, v241
	v_exp_f32_e32 v138, v138
	v_exp_f32_e32 v139, v139
	v_mfma_f32_32x32x16_bf16 v[32:47], v[164:167], v[84:87], v[32:47]
	v_fma_f32 v103, v14, s93, v242
	v_add_f32_e32 v240, v122, v240
	v_add_f32_e32 v241, v123, v241
	v_exp_f32_e32 v124, v124
	v_exp_f32_e32 v125, v125
	v_fma_f32 v104, v14, s90, v242
	v_mfma_f32_32x32x16_bf16 v[32:47], v[168:171], v[88:91], v[32:47]
	v_add_f32_e32 v240, v138, v240
	v_add_f32_e32 v241, v139, v241
	v_exp_f32_e32 v140, v140
	v_exp_f32_e32 v141, v141
	v_fma_f32 v105, v14, s91, v242
	v_add_f32_e32 v240, v124, v240
	v_mfma_f32_32x32x16_bf16 v[32:47], v[172:175], v[92:95], v[32:47]
	v_add_f32_e32 v241, v125, v241
	v_exp_f32_e32 v126, v126
	v_exp_f32_e32 v127, v127
	v_fma_f32 v106, v14, s88, v242
	v_add_f32_e32 v240, v140, v240
	v_add_f32_e32 v241, v141, v241
	ds_read_b128 v[160:163], v244 offset:4608
	ds_read_b128 v[164:167], v244 offset:4640
	ds_read_b128 v[168:171], v244 offset:4672
	ds_read_b128 v[172:175], v244 offset:4704
	s_waitcnt lgkmcnt(4)
	v_mfma_f32_32x32x16_bf16 v[16:31], v[224:227], v[80:83], v[16:31]
	v_exp_f32_e32 v142, v142
	v_exp_f32_e32 v143, v143
	v_fma_f32 v107, v14, s89, v242
	v_add_f32_e32 v240, v126, v240
	v_add_f32_e32 v241, v127, v241
	v_fma_f32 v108, v14, s86, v242
	v_mfma_f32_32x32x16_bf16 v[16:31], v[228:231], v[84:87], v[16:31]
	v_fma_f32 v109, v14, s87, v242
	v_fma_f32 v110, v14, s78, v242
	v_fma_f32 v111, v14, s79, v242
	v_mfma_f32_32x32x16_bf16 v[16:31], v[232:235], v[88:91], v[16:31]
	v_mfma_f32_32x32x16_bf16 v[16:31], v[236:239], v[92:95], v[16:31]
	ds_read_b128 v[224:227], v244 offset:0
	ds_read_b128 v[228:231], v244 offset:32
	ds_read_b128 v[232:235], v244 offset:64
	ds_read_b128 v[236:239], v244 offset:96
	s_waitcnt lgkmcnt(4)
	v_mfma_f32_32x32x16_bf16 v[96:111], v[160:163], v[2:5], v[96:111]
	v_mov_b32_e32 v80, v242
	v_add_f32_e32 v81, v14, v242
	v_fma_f32 v82, v14, s62, v242
	v_fma_f32 v83, v14, s63, v242
	v_mfma_f32_32x32x16_bf16 v[96:111], v[164:167], v[6:9], v[96:111]
	v_fma_f32 v84, v14, s64, v242
	v_fma_f32 v85, v14, s65, v242
	v_fma_f32 v86, v14, s66, v242
	v_fma_f32 v87, v14, s67, v242
	v_mfma_f32_32x32x16_bf16 v[96:111], v[168:171], v[10:13], v[96:111]
	v_fma_f32 v88, v14, s68, v242
	v_fma_f32 v89, v14, s69, v242
	v_fma_f32 v90, v14, s70, v242
	v_fma_f32 v91, v14, s71, v242
	v_mfma_f32_32x32x16_bf16 v[96:111], v[172:175], v[144:147], v[96:111]
	v_fma_f32 v92, v14, s72, v242
	v_fma_f32 v93, v14, s73, v242
	v_fma_f32 v94, v14, s76, v242
	v_fma_f32 v95, v14, s77, v242
	ds_read_b128 v[160:163], v251 offset:9216
	ds_read_b128 v[164:167], v251 offset:9248
	ds_read_b128 v[168:171], v251 offset:9280
	ds_read_b128 v[172:175], v251 offset:9312
	s_waitcnt lgkmcnt(4)
	v_mfma_f32_32x32x16_bf16 v[80:95], v[224:227], v[2:5], v[80:95]
	s_nop 0
	v_add_f32_e32 v240, v142, v240
	v_add_f32_e32 v241, v143, v241
	v_cvt_pk_bf16_f32 v112, v112, v113
	v_cvt_pk_bf16_f32 v113, v114, v115
	v_cvt_pk_bf16_f32 v114, v116, v117
	v_mfma_f32_32x32x16_bf16 v[80:95], v[228:231], v[6:9], v[80:95]
	v_cvt_pk_bf16_f32 v115, v118, v119
	v_cvt_pk_bf16_f32 v116, v120, v121
	v_cvt_pk_bf16_f32 v117, v122, v123
	v_cvt_pk_bf16_f32 v118, v124, v125
	v_cvt_pk_bf16_f32 v119, v126, v127
	v_cvt_pk_bf16_f32 v120, v128, v129
	v_mfma_f32_32x32x16_bf16 v[80:95], v[232:235], v[10:13], v[80:95]
	v_cvt_pk_bf16_f32 v121, v130, v131
	v_cvt_pk_bf16_f32 v122, v132, v133
	v_cvt_pk_bf16_f32 v123, v134, v135
	v_cvt_pk_bf16_f32 v124, v136, v137
	v_cvt_pk_bf16_f32 v125, v138, v139
	v_cvt_pk_bf16_f32 v126, v140, v141
	v_mfma_f32_32x32x16_bf16 v[80:95], v[236:239], v[144:147], v[80:95]
	v_cvt_pk_bf16_f32 v127, v142, v143
	v_add_f32_e32 v247, v240, v241
	v_add_f32_e32 v199, v199, v247
	s_branch .Ld_tail1
.Ld_gen1:
	s_add_i32 s12, s23, 2
	s_cmp_ge_i32 s12, s3
	s_cbranch_scc1 .Ld_nols_p1
	s_and_b32 s13, s12, 3
	s_mulk_i32 s13, 0x6c00
	s_waitcnt vmcnt(0)
	v_add_u32_e32 v248, s13, v204
	v_add_u32_e32 v249, s13, v200
	v_add_u32_e32 v250, s13, v202
	ds_write_b128 v248, v[148:151]
	ds_write_b128 v249, v[152:155] offset:9216
	ds_write_b128 v250, v[156:159] offset:9216
	s_add_i32 s12, s23, 3
	s_cmp_ge_i32 s12, s3
	s_cbranch_scc1 .Ld_nols_p1
	s_ashr_i32 s35, s34, 31
	s_lshl_b64 s[6:7], s[34:35], 17
	s_lshl_b64 s[10:11], s[34:35], 7
	s_add_u32 s10, s18, s10
	s_addc_u32 s11, s19, s11
	v_lshl_add_u64 v[246:247], v[206:207], 0, s[6:7]
	global_load_dwordx4 v[148:151], v[246:247], off
	v_lshl_add_u64 v[246:247], s[10:11], 0, v[0:1]
	global_load_dwordx4 v[152:155], v[246:247], off
	v_lshl_add_u64 v[246:247], s[10:11], 0, v[196:197]
	global_load_dwordx4 v[156:159], v[246:247], off
	s_add_i32 s34, s34, -1
.Ld_nols_p1:
	s_cmp_le_i32 s23, s24
	s_cbranch_scc1 .Ld_nopv_p1
	s_waitcnt lgkmcnt(0)
	s_add_i32 s12, s23, -1
	s_and_b32 s12, s12, 3
	s_mulk_i32 s12, 0x6c00
	v_add3_u32 v245, s12, v203, v194
	ds_read_b128 v[224:227], v245 offset:13824
	ds_read_b128 v[228:231], v245 offset:13856
	ds_read_b128 v[232:235], v245 offset:13888
	ds_read_b128 v[236:239], v245 offset:13920
	v_mfma_f32_32x32x16_bf16 v[64:79], v[160:163], v[80:83], v[64:79]
	v_mfma_f32_32x32x16_bf16 v[64:79], v[164:167], v[84:87], v[64:79]
	v_mfma_f32_32x32x16_bf16 v[64:79], v[168:171], v[88:91], v[64:79]
	v_mfma_f32_32x32x16_bf16 v[64:79], v[172:175], v[92:95], v[64:79]
	ds_read_b128 v[160:163], v245 offset:18432
	ds_read_b128 v[164:167], v245 offset:18464
	ds_read_b128 v[168:171], v245 offset:18496
	ds_read_b128 v[172:175], v245 offset:18528
	s_waitcnt lgkmcnt(4)
	v_mfma_f32_32x32x16_bf16 v[48:63], v[224:227], v[80:83], v[48:63]
	v_mfma_f32_32x32x16_bf16 v[48:63], v[228:231], v[84:87], v[48:63]
	v_mfma_f32_32x32x16_bf16 v[48:63], v[232:235], v[88:91], v[48:63]
	v_mfma_f32_32x32x16_bf16 v[48:63], v[236:239], v[92:95], v[48:63]
	ds_read_b128 v[224:227], v245 offset:23040
	ds_read_b128 v[228:231], v245 offset:23072
	ds_read_b128 v[232:235], v245 offset:23104
	ds_read_b128 v[236:239], v245 offset:23136
	s_waitcnt lgkmcnt(4)
	v_mfma_f32_32x32x16_bf16 v[32:47], v[160:163], v[80:83], v[32:47]
	v_mfma_f32_32x32x16_bf16 v[32:47], v[164:167], v[84:87], v[32:47]
	v_mfma_f32_32x32x16_bf16 v[32:47], v[168:171], v[88:91], v[32:47]
	v_mfma_f32_32x32x16_bf16 v[32:47], v[172:175], v[92:95], v[32:47]
	s_waitcnt lgkmcnt(0)
	v_mfma_f32_32x32x16_bf16 v[16:31], v[224:227], v[80:83], v[16:31]
	v_mfma_f32_32x32x16_bf16 v[16:31], v[228:231], v[84:87], v[16:31]
	v_mfma_f32_32x32x16_bf16 v[16:31], v[232:235], v[88:91], v[16:31]
	v_mfma_f32_32x32x16_bf16 v[16:31], v[236:239], v[92:95], v[16:31]
